# norm phases keep gain (once) and per-batch scale/shift vectors in registers instead of reloading 12 KB per row; conv phase keeps its 12 weight quads in registers
# speedup vs baseline: 1.2353x; 1.0094x over previous
.LBB0_204:
	s_or_b64 exec, exec, s[4:5]
	v_mov_b32_e32 v2, v202
	s_waitcnt lgkmcnt(0)
	s_barrier
	s_nop 0
	s_nop 0
	s_nop 0
	s_nop 0
	s_nop 0
	s_nop 0
	s_nop 0
	s_nop 0
	s_nop 0
	s_nop 0
	s_nop 0
	s_nop 0
	s_nop 0
	s_nop 0
	s_nop 0
	s_nop 0
	s_nop 0
	s_nop 0
	s_nop 0
	s_nop 0
	s_nop 0
	s_nop 0
	s_nop 0
	s_nop 0
	s_nop 0
	s_nop 0
	s_nop 0
	s_nop 0
	s_nop 0
	s_nop 0
	s_nop 0
	s_nop 0
	s_nop 0
	s_nop 0
	s_nop 0
	s_nop 0
	s_nop 0
	s_nop 0
	s_nop 0
	s_nop 0
	s_nop 0
	s_nop 0
	s_nop 0
	s_nop 0
	s_nop 0
	s_nop 0
	s_nop 0
	s_nop 0
	s_nop 0
	s_nop 0
	s_nop 0
	s_nop 0
	v_mbcnt_lo_u32_b32 v1, -1, 0
	v_readfirstlane_b32 s4, v2
	s_ashr_i32 s4, s4, 6
	s_add_i32 s4, s4, s76
	s_cmpk_gt_i32 s4, 0x7fff
	s_cbranch_scc1 .LBB0_207
	s_load_dwordx2 s[6:7], s[0:1], 0x0
	s_load_dwordx2 s[8:9], s[0:1], 0x28
	s_add_u32 s12, s28, 0x3100000
	s_addc_u32 s13, s29, 0
	s_ashr_i32 s5, s4, 31
	s_lshl_b64 s[10:11], s[4:5], 12
	v_and_b32_e32 v21, 63, v2
	s_waitcnt lgkmcnt(0)
	s_add_u32 s10, s6, s10
	s_addc_u32 s11, s7, s11
	v_lshlrev_b32_e32 v18, 4, v21
	global_load_dwordx4 v[2:5], v18, s[10:11] offset:3072
	global_load_dwordx4 v[6:9], v18, s[10:11] offset:2048
	global_load_dwordx4 v[14:17], v18, s[10:11]
	global_load_dwordx4 v[10:13], v18, s[10:11] offset:1024
	v_mbcnt_hi_u32_b32 v25, -1, v1
	v_and_b32_e32 v24, 64, v25
	v_xor_b32_e32 v27, 1, v25
	v_add_u32_e32 v35, 64, v24
	v_xor_b32_e32 v29, 2, v25
	v_lshlrev_b32_e32 v20, 2, v21
	v_cmp_lt_i32_e32 vcc, v27, v35
	v_xor_b32_e32 v31, 4, v25
	v_or_b32_e32 v24, 0x100, v20
	v_or_b32_e32 v26, 0x200, v20
	v_or_b32_e32 v28, 0x300, v20
	v_lshlrev_b32_e32 v30, 2, v20
	v_cndmask_b32_e32 v20, v25, v27, vcc
	v_cmp_lt_i32_e32 vcc, v29, v35
	v_xor_b32_e32 v32, 8, v25
	v_xor_b32_e32 v33, 16, v25
	v_cndmask_b32_e32 v27, v25, v29, vcc
	v_cmp_lt_i32_e32 vcc, v31, v35
	v_xor_b32_e32 v34, 32, v25
	v_mov_b32_e32 v19, 0
	v_cndmask_b32_e32 v29, v25, v31, vcc
	v_cmp_lt_i32_e32 vcc, v32, v35
	v_lshlrev_b32_e32 v31, 2, v24
	s_mov_b64 s[10:11], 0x4000000
	v_cndmask_b32_e32 v37, v25, v32, vcc
	v_cmp_lt_i32_e32 vcc, v33, v35
	v_lshlrev_b32_e32 v32, 2, v26
	v_mov_b32_e32 v23, 0x358637bd
	v_cndmask_b32_e32 v38, v25, v33, vcc
	v_cmp_lt_i32_e32 vcc, v34, v35
	v_lshlrev_b32_e32 v35, 2, v27
	v_lshl_add_u64 v[26:27], s[8:9], 0, v[18:19]
	v_cndmask_b32_e32 v25, v25, v34, vcc
	v_lshlrev_b32_e32 v39, 2, v25
	v_lshl_add_u64 v[24:25], s[6:7], 0, v[18:19]
	s_lshl_b64 s[6:7], s[4:5], 11
	s_add_u32 s6, s28, s6
	v_lshlrev_b32_e32 v18, 3, v21
	s_addc_u32 s7, s29, s7
	s_ashr_i32 s37, s36, 31
	v_lshl_add_u64 v[18:19], s[6:7], 0, v[18:19]
	s_mov_b32 s14, 0x800000
	v_lshlrev_b32_e32 v33, 2, v28
	v_lshlrev_b32_e32 v34, 2, v20
	v_lshlrev_b32_e32 v36, 2, v29
	v_lshlrev_b32_e32 v37, 2, v37
	v_lshlrev_b32_e32 v38, 2, v38
	s_lshl_b64 s[6:7], s[36:37], 11
	v_lshl_add_u64 v[28:29], v[18:19], 0, s[10:11]
	s_waitcnt vmcnt(3)
	v_mov_b32_e32 v18, v2
	v_mov_b32_e32 v19, v3
	v_mov_b32_e32 v20, v4
	v_mov_b32_e32 v21, v5
	s_mov_b32 s98, -1
	global_load_dwordx4 v[104:107], v[26:27], off
	global_load_dwordx4 v[68:71], v[26:27], off offset:1024
	global_load_dwordx4 v[80:83], v[26:27], off offset:2048
	global_load_dwordx4 v[92:95], v[26:27], off offset:3072
.LBB0_206:
	s_ashr_i32 s5, s4, 13
	s_mov_b32 s99, s5
	s_mul_i32 s8, s5, 0x1800
	s_ashr_i32 s9, s8, 31
	s_lshl_b64 s[8:9], s[8:9], 2
	s_add_u32 s8, s12, s8
	s_addc_u32 s9, s13, s9
	s_add_i32 s15, s4, s36
	s_cmp_lt_i32 s15, 0x8000
	s_cselect_b64 s[10:11], -1, 0
	s_and_b64 vcc, s[10:11], exec
	s_cselect_b32 s4, s15, s4
	s_ashr_i32 s5, s4, 31
	s_waitcnt vmcnt(0)
	v_pk_mul_f32 v[44:45], v[12:13], v[12:13]
	v_pk_mul_f32 v[46:47], v[10:11], v[10:11]
	v_pk_mul_f32 v[48:49], v[16:17], v[16:17]
	v_pk_mul_f32 v[50:51], v[14:15], v[14:15]
	s_lshl_b64 s[4:5], s[4:5], 12
	v_mul_f32_e32 v52, v6, v6
	v_mul_f32_e32 v54, v8, v8
	v_pk_mov_b32 v[56:57], v[50:51], v[48:49] op_sel:[1,0]
	v_mov_b32_e32 v51, v49
	v_pk_mov_b32 v[48:49], v[46:47], v[44:45] op_sel:[1,0]
	v_mov_b32_e32 v47, v45
	s_add_u32 s10, s8, 0x1000
	v_pk_fma_f32 v[52:53], v[6:7], v[6:7], v[52:53] op_sel_hi:[1,1,0]
	v_pk_fma_f32 v[54:55], v[8:9], v[8:9], v[54:55] op_sel_hi:[1,1,0]
	v_pk_add_f32 v[44:45], v[56:57], v[50:51]
	v_pk_add_f32 v[46:47], v[48:49], v[46:47]
	s_addc_u32 s11, s9, 0
	v_mul_f32_e32 v52, v18, v18
	v_mul_f32_e32 v54, v19, v19
	v_pk_add_f32 v[18:19], v[44:45], v[44:45] op_sel_hi:[0,1]
	v_pk_add_f32 v[56:57], v[46:47], v[46:47] op_sel_hi:[0,1]
	s_cmp_eq_u32 s99, s98
	s_cbranch_scc1 .Lnorm_keep_0
	s_mov_b32 s98, s99
	global_load_dwordx4 v[108:111], v30, s[10:11]
	global_load_dwordx4 v[112:115], v30, s[8:9]
	global_load_dwordx4 v[72:75], v31, s[10:11]
	global_load_dwordx4 v[76:79], v30, s[8:9] offset:1024
	global_load_dwordx4 v[84:87], v32, s[10:11]
	global_load_dwordx4 v[88:91], v30, s[8:9] offset:2048
	global_load_dwordx4 v[96:99], v33, s[10:11]
	global_load_dwordx4 v[100:103], v30, s[8:9] offset:3072
.Lnorm_keep_0:
	v_mul_f32_e32 v18, v20, v20
	v_mul_f32_e32 v56, v21, v21
	v_pk_add_f32 v[52:53], v[52:53], v[54:55]
	v_pk_add_f32 v[18:19], v[18:19], v[56:57]
	v_lshl_add_u64 v[64:65], v[24:25], 0, s[4:5]
	v_pk_add_f32 v[18:19], v[52:53], v[18:19]
	s_nop 0
	v_add_f32_e32 v66, v18, v19
	ds_bpermute_b32 v67, v34, v66
	global_load_dwordx4 v[52:55], v[64:65], off
	global_load_dwordx4 v[56:59], v[64:65], off offset:1024
	global_load_dwordx4 v[60:63], v[64:65], off offset:2048
	global_load_dwordx4 v[18:21], v[64:65], off offset:3072
	s_waitcnt lgkmcnt(0)
	v_add_f32_e32 v64, v66, v67
	ds_bpermute_b32 v65, v35, v64
	s_waitcnt lgkmcnt(0)
	v_add_f32_e32 v64, v64, v65
	ds_bpermute_b32 v65, v36, v64
	s_waitcnt lgkmcnt(0)
	v_add_f32_e32 v64, v64, v65
	ds_bpermute_b32 v65, v37, v64
	s_waitcnt lgkmcnt(0)
	v_add_f32_e32 v64, v64, v65
	ds_bpermute_b32 v65, v38, v64
	s_waitcnt lgkmcnt(0)
	v_add_f32_e32 v64, v64, v65
	ds_bpermute_b32 v65, v39, v64
	s_waitcnt lgkmcnt(0)
	v_add_f32_e32 v64, v64, v65
	v_fmamk_f32 v64, v64, 0x3a800000, v23
	v_mul_f32_e32 v65, 0x4b800000, v64
	v_cmp_gt_f32_e64 s[4:5], s14, v64
	s_nop 1
	v_cndmask_b32_e64 v64, v64, v65, s[4:5]
	v_rsq_f32_e32 v64, v64
	s_nop 0
	v_mul_f32_e32 v65, 0x45800000, v64
	v_cndmask_b32_e64 v64, v64, v65, s[4:5]
	v_pk_mul_f32 v[16:17], v[16:17], v[64:65] op_sel_hi:[1,0]
	v_pk_mul_f32 v[14:15], v[14:15], v[64:65] op_sel_hi:[1,0]
	v_pk_mul_f32 v[12:13], v[12:13], v[64:65] op_sel_hi:[1,0]
	v_pk_mul_f32 v[10:11], v[10:11], v[64:65] op_sel_hi:[1,0]
	v_pk_mul_f32 v[8:9], v[8:9], v[64:65] op_sel_hi:[1,0]
	v_pk_mul_f32 v[6:7], v[6:7], v[64:65] op_sel_hi:[1,0]
	v_pk_mul_f32 v[66:67], v[4:5], v[64:65] op_sel_hi:[1,0]
	v_pk_mul_f32 v[64:65], v[2:3], v[64:65] op_sel_hi:[1,0]
	s_mov_b32 s4, s15
	s_waitcnt vmcnt(4)
	v_pk_mul_f32 v[14:15], v[104:105], v[14:15]
	v_pk_mul_f32 v[16:17], v[106:107], v[16:17]
	v_pk_add_f32 v[42:43], v[108:109], 1.0 op_sel_hi:[1,0]
	v_pk_add_f32 v[40:41], v[110:111], 1.0 op_sel_hi:[1,0]
	v_pk_fma_f32 v[14:15], v[42:43], v[14:15], v[112:113]
	v_pk_fma_f32 v[16:17], v[40:41], v[16:17], v[114:115]
	v_cvt_pk_bf16_f32 v14, v14, v15
	s_waitcnt vmcnt(0)
	v_mov_b64_e32 v[2:3], v[18:19]
	v_cvt_pk_bf16_f32 v15, v16, v17
	global_store_dwordx2 v[28:29], v[14:15], off
	v_mov_b64_e32 v[4:5], v[20:21]
	s_waitcnt vmcnt(1)
	v_pk_mul_f32 v[10:11], v[68:69], v[10:11]
	v_pk_mul_f32 v[12:13], v[70:71], v[12:13]
	v_pk_add_f32 v[16:17], v[72:73], 1.0 op_sel_hi:[1,0]
	v_pk_add_f32 v[14:15], v[74:75], 1.0 op_sel_hi:[1,0]
	v_pk_fma_f32 v[10:11], v[16:17], v[10:11], v[76:77]
	v_pk_fma_f32 v[12:13], v[14:15], v[12:13], v[78:79]
	v_cvt_pk_bf16_f32 v10, v10, v11
	s_nop 0
	v_cvt_pk_bf16_f32 v11, v12, v13
	global_store_dwordx2 v[28:29], v[10:11], off offset:512
	s_waitcnt vmcnt(2)
	v_pk_mul_f32 v[6:7], v[6:7], v[80:81]
	v_pk_mul_f32 v[8:9], v[8:9], v[82:83]
	v_pk_add_f32 v[12:13], v[84:85], 1.0 op_sel_hi:[1,0]
	v_pk_add_f32 v[10:11], v[86:87], 1.0 op_sel_hi:[1,0]
	v_pk_fma_f32 v[6:7], v[6:7], v[12:13], v[88:89]
	v_pk_fma_f32 v[8:9], v[8:9], v[10:11], v[90:91]
	v_cvt_pk_bf16_f32 v6, v6, v7
	v_mov_b32_e32 v14, v52
	v_cvt_pk_bf16_f32 v7, v8, v9
	global_store_dwordx2 v[28:29], v[6:7], off offset:1024
	v_mov_b32_e32 v15, v53
	v_mov_b32_e32 v16, v54
	v_mov_b32_e32 v17, v55
	v_mov_b32_e32 v10, v56
	v_mov_b32_e32 v11, v57
	v_mov_b32_e32 v12, v58
	v_mov_b32_e32 v13, v59
	v_mov_b32_e32 v6, v60
	v_mov_b32_e32 v7, v61
	v_mov_b32_e32 v8, v62
	v_mov_b32_e32 v9, v63
	s_waitcnt vmcnt(3)
	v_pk_mul_f32 v[40:41], v[64:65], v[92:93]
	v_pk_add_f32 v[44:45], v[96:97], 1.0 op_sel_hi:[1,0]
	v_pk_mul_f32 v[42:43], v[66:67], v[94:95]
	v_pk_add_f32 v[46:47], v[98:99], 1.0 op_sel_hi:[1,0]
	v_pk_fma_f32 v[40:41], v[40:41], v[44:45], v[100:101]
	v_pk_fma_f32 v[42:43], v[42:43], v[46:47], v[102:103]
	v_cvt_pk_bf16_f32 v40, v40, v41
	s_nop 0
	v_cvt_pk_bf16_f32 v41, v42, v43
	global_store_dwordx2 v[28:29], v[40:41], off offset:1536
	v_lshl_add_u64 v[28:29], v[28:29], 0, s[6:7]
	s_cbranch_vccnz .LBB0_206

.LBB0_259:
	s_or_b64 exec, exec, s[4:5]
	s_cmpk_lt_i32 s2, 0x480
	s_cselect_b64 s[4:5], -1, 0
	s_cmpk_gt_i32 s2, 0x47f
	v_readfirstlane_b32 s6, v202
	s_waitcnt lgkmcnt(0)
	s_barrier
	s_nop 0
	s_nop 0
	s_nop 0
	s_nop 0
	s_nop 0
	s_cbranch_scc1 .LBB0_261
	s_ashr_i32 s7, s2, 31
	s_lshr_b32 s7, s7, 29
	s_add_i32 s7, s2, s7
	s_ashr_i32 s8, s7, 3
	s_and_b32 s7, s7, -8
	s_sub_i32 s7, s2, s7
	s_cmp_lt_i32 s7, 0
	s_movk_i32 s9, 0x91
	s_cselect_b32 s9, s9, 0x90
	s_mul_i32 s7, s9, s7
	s_add_i32 s7, s7, s8
	s_mul_hi_i32 s8, s7, 0x38e38e39
	s_lshr_b32 s9, s8, 31
	s_ashr_i32 s8, s8, 4
	s_add_i32 s8, s8, s9
	s_lshl_b32 s9, s8, 3
	s_mulk_i32 s8, 0x48
	s_sub_i32 s7, s7, s8
	s_bfe_i32 s8, s7, 0x80000
	s_bfe_u32 s8, s8, 0x3000c
	s_add_i32 s8, s7, s8
	s_bfe_i32 s10, s8, 0x80000
	s_and_b32 s8, s8, 0xf8
	s_sub_i32 s7, s7, s8
	s_sext_i32_i16 s10, s10
	s_sext_i32_i8 s7, s7
	s_add_i32 s8, s9, s7
	s_ashr_i32 s68, s10, 3

.LBB0_975:
	s_or_b64 exec, exec, s[4:5]
	v_mov_b32_e32 v15, v202
	s_add_u32 s62, s28, 0x14000000
	s_waitcnt lgkmcnt(0)
	s_barrier
	s_nop 0
	s_nop 0
	s_nop 0
	s_nop 0
	s_nop 0
	s_nop 0
	s_nop 0
	s_nop 0
	s_nop 0
	s_nop 0
	s_nop 0
	s_nop 0
	s_nop 0
	s_nop 0
	s_nop 0
	s_nop 0
	s_nop 0
	s_nop 0
	s_nop 0
	s_nop 0
	s_nop 0
	s_nop 0
	s_nop 0
	s_nop 0
	s_nop 0
	s_nop 0
	s_nop 0
	s_nop 0
	s_nop 0
	s_nop 0
	s_nop 0
	s_nop 0
	s_nop 0
	s_nop 0
	s_nop 0
	s_nop 0
	s_nop 0
	s_nop 0
	s_nop 0
	s_nop 0
	s_nop 0
	s_nop 0
	s_nop 0
	s_nop 0
	s_nop 0
	s_nop 0
	s_nop 0
	s_nop 0
	s_nop 0
	s_nop 0
	s_nop 0
	s_nop 0
	s_nop 0
	s_nop 0
	s_addc_u32 s63, s29, 0
	v_readfirstlane_b32 s4, v15
	s_ashr_i32 s4, s4, 6
	s_and_b64 s[6:7], s[46:47], exec
	s_cselect_b32 s5, 8, 1
	v_cvt_f32_ubyte0_e32 v1, s5
	v_rcp_iflag_f32_e32 v1, v1
	s_add_i32 s8, s5, -1
	s_and_b64 s[6:7], s[46:47], exec
	s_cselect_b32 s24, 3, 0
	v_mul_f32_e32 v1, 0x4f7ffffe, v1
	v_cvt_u32_f32_e32 v1, v1
	s_sub_i32 s9, 0, s5
	s_abs_i32 s7, s30
	s_lshr_b32 s6, s2, s24
	v_readfirstlane_b32 s10, v1
	s_mul_i32 s9, s9, s10
	s_mul_hi_u32 s9, s10, s9
	s_add_i32 s10, s10, s9
	s_mul_hi_u32 s9, s7, s10
	s_mul_i32 s10, s9, s5
	s_sub_i32 s7, s7, s10
	s_lshl_b32 s6, s6, 3
	s_ashr_i32 s68, s30, 31
	s_add_i32 s10, s9, 1
	s_sub_i32 s11, s7, s5
	s_cmp_ge_u32 s7, s5
	s_cselect_b32 s9, s10, s9
	s_cselect_b32 s7, s11, s7
	s_add_i32 s10, s9, 1
	s_cmp_ge_u32 s7, s5
	s_cselect_b32 s7, s10, s9
	s_xor_b32 s7, s7, s68
	s_sub_i32 s7, s7, s68
	s_lshl_b32 s25, s7, 3
	s_abs_i32 s7, s25
	v_cvt_f32_u32_e32 v1, s7
	s_add_i32 s40, s4, s6
	s_sub_i32 s6, s25, s40
	s_and_b32 s41, s8, s2
	v_rcp_iflag_f32_e32 v1, v1
	s_add_i32 s8, s6, 0x1fff
	s_sub_i32 s6, 0xffffe001, s6
	s_xor_b32 s9, s8, s25
	v_mul_f32_e32 v1, 0x4f7ffffe, v1
	v_cvt_u32_f32_e32 v1, v1
	s_max_i32 s6, s8, s6
	s_sub_i32 s8, 0, s7
	s_ashr_i32 s9, s9, 31
	v_readfirstlane_b32 s10, v1
	s_mul_i32 s8, s8, s10
	s_mul_hi_u32 s8, s10, s8
	s_add_i32 s10, s10, s8
	s_mul_hi_u32 s8, s6, s10
	s_mul_i32 s10, s8, s7
	s_sub_i32 s6, s6, s10
	s_add_i32 s10, s8, 1
	s_sub_i32 s11, s6, s7
	s_cmp_ge_u32 s6, s7
	s_cselect_b32 s8, s10, s8
	s_cselect_b32 s6, s11, s6
	s_add_i32 s10, s8, 1
	s_cmp_ge_u32 s6, s7
	s_cselect_b32 s6, s10, s8
	s_sub_i32 s5, s5, s41
	s_xor_b32 s6, s6, s9
	s_add_i32 s5, s5, 15
	s_sub_i32 s42, s6, s9
	s_lshr_b32 s5, s5, s24
	s_mul_i32 s43, s42, s5
	s_cmp_lt_i32 s43, 1
	s_mov_b32 s9, 0
	s_cbranch_scc1 .LBB0_980
	s_lshl_b32 s5, s4, 14
	s_lshl_b32 s4, s4, 10
	s_add_i32 s47, s4, 0
	s_lshr_b32 s8, s41, 2
	s_add_i32 s46, s5, 0
	s_add_i32 s47, s47, 0x20000
	s_and_b32 s10, s41, 3
	s_lshl_b64 s[4:5], s[8:9], 13
	s_ashr_i32 s6, s40, 31
	s_add_u32 s4, s4, s40
	s_addc_u32 s5, s5, s6
	s_lshl_b64 s[6:7], s[4:5], 9
	v_and_b32_e32 v14, 63, v15
	s_add_u32 s6, s44, s6
	s_addc_u32 s7, s45, s7
	v_lshlrev_b32_e32 v42, 3, v14
	global_load_dwordx2 v[2:3], v42, s[6:7]
	v_and_b32_e32 v17, 15, v15
	v_bfe_u32 v4, v15, 4, 2
	v_bfe_u32 v6, v15, 2, 2
	v_and_b32_e32 v1, 7, v15
	v_lshlrev_b32_e32 v34, 3, v15
	v_mov_b32_e32 v7, 0x1000
	v_lshrrev_b32_e32 v9, 3, v15
	v_or_b32_e32 v12, 16, v17
	v_lshl_or_b32 v6, v4, 2, v6
	v_bfe_u32 v5, v15, 3, 1
	v_and_b32_e32 v10, 1, v15
	v_bitop3_b32 v13, v4, v1, 4 bitop3:0x36
	v_bitop3_b32 v16, v4, v15, 7 bitop3:0x78
	v_and_or_b32 v7, v34, 24, v7
	v_xor_b32_e32 v9, v9, v15
	v_mul_u32_u24_e32 v21, 0x40004, v14
	v_lshrrev_b32_e32 v22, 3, v12
	v_lshlrev_b32_e32 v24, 4, v6
	v_lshlrev_b32_e32 v6, 7, v6
	s_cmpk_gt_i32 s40, 0xff
	s_movk_i32 s6, 0x60
	v_lshlrev_b32_e32 v12, 7, v12
	v_xor_b32_e32 v23, v13, v5
	v_xor_b32_e32 v5, v16, v5
	v_and_or_b32 v9, v9, 6, v10
	v_or_b32_e32 v60, 0x10000, v21
	v_or_b32_e32 v61, 0x30002, v21
	v_xor_b32_e32 v10, v13, v22
	v_xor_b32_e32 v13, v16, v22
	v_or_b32_e32 v16, 0x800, v6
	v_or_b32_e32 v6, v6, v7
	s_cselect_b64 vcc, -1, 0
	v_lshlrev_b32_e32 v11, 6, v15
	s_waitcnt vmcnt(2)
	v_lshlrev_b32_e32 v52, 4, v9
	v_add_u32_e32 v9, s47, v42
	v_lshl_or_b32 v37, v10, 4, v12
	v_bitop3_b32 v10, v24, v16, s6 bitop3:0xce
	v_bitop3_b32 v39, v24, v6, s6 bitop3:0xce
	s_mul_hi_u32 s6, s4, 0x1200
	s_mulk_i32 s5, 0x1200
	s_mulk_i32 s4, 0x1200
	s_add_i32 s6, s6, s5
	v_mov_b32_e32 v43, 0
	s_add_u32 s4, s38, s4
	v_mov_b32_e32 v8, 0x60
	v_lshlrev_b32_e32 v19, 7, v17
	s_addc_u32 s5, s39, s6
	v_lshl_or_b32 v35, v23, 4, v19
	v_lshl_or_b32 v36, v5, 4, v19
	v_and_b32_e32 v5, 0x60, v24
	v_bitop3_b32 v19, v24, 64, v8 bitop3:0x6c
	v_bitop3_b32 v8, v24, 32, v8 bitop3:0x6c
	v_bfe_u32 v18, v15, 3, 3
	v_lshl_or_b32 v38, v13, 4, v12
	v_or_b32_e32 v12, v19, v16
	v_or_b32_e32 v13, v8, v16
	v_or_b32_e32 v41, v8, v6
	v_or_b32_e32 v8, v5, v16
	s_waitcnt vmcnt(1)
	v_or_b32_e32 v56, v6, v5
	v_lshlrev_b32_e32 v16, 3, v4
	v_and_b32_e32 v4, 48, v15
	v_mov_b32_e32 v5, v43
	v_lshlrev_b32_e32 v63, 6, v18
	v_bitop3_b32 v20, v18, v15, 7 bitop3:0x78
	v_or_b32_e32 v40, v19, v6
	v_add_u32_e32 v57, v10, v7
	v_add_u32_e32 v58, v12, v7
	v_add_u32_e32 v59, v13, v7
	v_add_u32_e32 v90, v8, v7
	v_add_u32_e32 v18, s47, v63
	v_mov_b32_e32 v19, v43
	v_lshlrev_b32_e32 v44, 4, v20
	v_mov_b32_e32 v45, v43
	s_mov_b32 m0, s46
	v_mov_b32_e32 v53, v43
	v_mov_b32_e32 v64, 9
	v_xor_b32_e32 v50, 16, v44
	v_mov_b32_e32 v51, v43
	v_xor_b32_e32 v48, 32, v44
	s_waitcnt vmcnt(0)
	v_cndmask_b32_e32 v2, v60, v2, vcc
	v_cndmask_b32_e32 v3, v61, v3, vcc
	ds_write_b64 v9, v[2:3]
	v_and_b32_e32 v2, 0xc0, v11
	v_lshlrev_b32_e32 v62, 1, v2
	v_lshl_or_b32 v2, s10, 9, v62
	v_mov_b32_e32 v3, v43
	v_lshl_add_u64 v[2:3], s[4:5], 0, v[2:3]
	s_lshl_b64 s[4:5], s[8:9], 22
	s_add_u32 s6, s80, s4
	v_lshl_add_u64 v[2:3], v[2:3], 0, v[4:5]
	s_addc_u32 s7, s81, s5
	global_load_dwordx4 v[10:13], v[2:3], off
	global_load_dwordx4 v[6:9], v[2:3], off offset:64
	s_waitcnt lgkmcnt(0)
	s_add_u32 s4, s37, s4
	ds_read_b128 v[30:33], v18
	ds_read_b128 v[22:25], v18 offset:16
	ds_read_b128 v[2:5], v18 offset:32
	ds_read_b128 v[26:29], v18 offset:48
	s_addc_u32 s5, s79, s5
	s_lshl_b32 s8, s10, 7
	s_add_u32 s4, s4, s8
	s_addc_u32 s5, s5, 0
	s_waitcnt lgkmcnt(3)
	v_lshlrev_b32_e32 v18, 9, v30
	s_add_u32 s6, s6, s8
	v_and_b32_e32 v18, 0x1fffe00, v18
	s_addc_u32 s7, s7, 0
	v_lshl_add_u64 v[20:21], s[4:5], 0, v[18:19]
	s_add_i32 s48, s46, 0x1000
	v_lshl_add_u64 v[20:21], v[20:21], 0, v[44:45]
	v_lshl_add_u64 v[18:19], s[6:7], 0, v[18:19]
	global_load_lds_dwordx4 v[20:21], off
	v_lshl_add_u64 v[18:19], v[18:19], 0, v[52:53]
	s_mov_b32 m0, s48
	s_add_i32 s49, s46, 0x400
	global_load_lds_dwordx4 v[18:19], off
	v_lshlrev_b32_sdwa v18, v64, v30 dst_sel:DWORD dst_unused:UNUSED_PAD src0_sel:DWORD src1_sel:WORD_1
	v_mov_b32_e32 v19, v43
	v_lshl_add_u64 v[20:21], s[4:5], 0, v[18:19]
	v_lshl_add_u64 v[20:21], v[20:21], 0, v[50:51]
	s_mov_b32 m0, s49
	v_lshl_add_u64 v[18:19], s[6:7], 0, v[18:19]
	s_add_i32 s50, s46, 0x1400
	global_load_lds_dwordx4 v[20:21], off
	v_lshl_add_u64 v[18:19], v[18:19], 0, v[52:53]
	s_mov_b32 m0, s50
	v_mov_b32_e32 v49, v43
	global_load_lds_dwordx4 v[18:19], off
	v_lshlrev_b32_e32 v18, 9, v31
	v_and_b32_e32 v18, 0x1fffe00, v18
	v_mov_b32_e32 v19, v43
	v_lshl_add_u64 v[20:21], s[4:5], 0, v[18:19]
	s_add_i32 s51, s46, 0x800
	v_lshl_add_u64 v[20:21], v[20:21], 0, v[48:49]
	s_mov_b32 m0, s51
	v_lshl_add_u64 v[18:19], s[6:7], 0, v[18:19]
	s_add_i32 s52, s46, 0x1800
	global_load_lds_dwordx4 v[20:21], off
	v_lshl_add_u64 v[18:19], v[18:19], 0, v[52:53]
	s_mov_b32 m0, s52
	v_xor_b32_e32 v46, 48, v44
	global_load_lds_dwordx4 v[18:19], off
	v_lshlrev_b32_sdwa v18, v64, v31 dst_sel:DWORD dst_unused:UNUSED_PAD src0_sel:DWORD src1_sel:WORD_1
	v_mov_b32_e32 v19, v43
	v_lshl_add_u64 v[20:21], s[4:5], 0, v[18:19]
	v_mov_b32_e32 v47, v43
	s_add_i32 s53, s46, 0xc00
	v_lshl_add_u64 v[20:21], v[20:21], 0, v[46:47]
	s_mov_b32 m0, s53
	v_lshl_add_u64 v[18:19], s[6:7], 0, v[18:19]
	s_add_i32 s54, s46, 0x1c00
	global_load_lds_dwordx4 v[20:21], off
	v_lshl_add_u64 v[18:19], v[18:19], 0, v[52:53]
	s_mov_b32 m0, s54
	v_cmp_gt_u32_e64 s[4:5], 4, v17
	global_load_lds_dwordx4 v[18:19], off
	v_and_b32_e32 v17, 0x80, v34
	v_bfe_u32 v15, v15, 5, 1
	v_or_b32_e32 v19, 32, v17
	v_or_b32_e32 v20, 64, v17
	v_or_b32_e32 v21, 0x60, v17
	v_or_b32_e32 v30, 6, v15
	v_or_b32_e32 v82, v17, v30
	v_or_b32_e32 v84, v19, v30
	v_or_b32_e32 v86, v20, v30
	v_or_b32_e32 v88, v21, v30
	v_or_b32_e32 v30, 10, v15
	v_or_b32_e32 v18, 2, v15
	v_or_b32_e32 v98, v17, v30
	v_or_b32_e32 v100, v19, v30
	v_or_b32_e32 v102, v20, v30
	v_or_b32_e32 v104, v21, v30
	v_or_b32_e32 v30, 14, v15
	v_or_b32_e32 v66, v17, v18
	v_or_b32_e32 v68, v19, v18
	v_or_b32_e32 v70, v20, v18
	v_or_b32_e32 v72, v21, v18
	v_or_b32_e32 v18, 4, v15
	v_or_b32_e32 v106, v17, v30
	v_or_b32_e32 v108, v19, v30
	v_or_b32_e32 v110, v20, v30
	v_or_b32_e32 v112, v21, v30
	v_or_b32_e32 v30, 18, v15
	v_or_b32_e32 v81, v17, v18
	v_or_b32_e32 v83, v19, v18
	v_or_b32_e32 v85, v20, v18
	v_or_b32_e32 v87, v21, v18
	v_or_b32_e32 v18, 8, v15
	v_or_b32_e32 v114, v17, v30
	v_or_b32_e32 v116, v19, v30
	v_or_b32_e32 v118, v20, v30
	v_or_b32_e32 v120, v21, v30
	v_or_b32_e32 v30, 22, v15
	v_lshl_add_u64 v[54:55], s[44:45], 0, v[42:43]
	v_or_b32_e32 v97, v17, v18
	v_or_b32_e32 v99, v19, v18
	v_or_b32_e32 v101, v20, v18
	v_or_b32_e32 v103, v21, v18
	v_or_b32_e32 v18, 12, v15
	v_or_b32_e32 v122, v17, v30
	v_or_b32_e32 v124, v19, v30
	v_or_b32_e32 v126, v20, v30
	v_or_b32_e32 v128, v21, v30
	v_or_b32_e32 v30, 26, v15
	s_abs_i32 s45, s42
	v_or_b32_e32 v105, v17, v18
	v_or_b32_e32 v107, v19, v18
	v_or_b32_e32 v109, v20, v18
	v_or_b32_e32 v111, v21, v18
	v_or_b32_e32 v18, 16, v15
	v_or_b32_e32 v130, v17, v30
	v_or_b32_e32 v132, v19, v30
	v_or_b32_e32 v134, v20, v30
	v_or_b32_e32 v136, v21, v30
	v_cvt_f32_u32_e32 v30, s45
	v_or_b32_e32 v113, v17, v18
	v_or_b32_e32 v115, v19, v18
	v_or_b32_e32 v117, v20, v18
	v_or_b32_e32 v119, v21, v18
	v_or_b32_e32 v18, 20, v15
	v_or_b32_e32 v121, v17, v18
	v_or_b32_e32 v123, v19, v18
	v_or_b32_e32 v125, v20, v18
	v_or_b32_e32 v127, v21, v18
	v_or_b32_e32 v18, 24, v15
	v_or_b32_e32 v65, v17, v15
	v_or_b32_e32 v67, v19, v15
	v_or_b32_e32 v69, v20, v15
	v_or_b32_e32 v71, v21, v15
	v_or_b32_e32 v129, v17, v18
	v_or_b32_e32 v131, v19, v18
	v_or_b32_e32 v133, v20, v18
	v_or_b32_e32 v135, v21, v18
	v_or_b32_e32 v18, 28, v15
	v_or_b32_e32 v15, 30, v15
	v_or_b32_e32 v137, v17, v18
	v_or_b32_e32 v138, v17, v15
	v_rcp_iflag_f32_e32 v17, v30
	s_sub_i32 s8, 0, s45
	s_add_i32 s44, s46, 0x2000
	v_lshlrev_b32_e32 v1, 2, v14
	v_mul_f32_e32 v17, 0x4f7ffffe, v17
	v_cvt_u32_f32_e32 v17, v17
	s_waitcnt vmcnt(0)
	v_cndmask_b32_e64 v9, 0, v9, s[4:5]
	v_cndmask_b32_e64 v8, 0, v8, s[4:5]
	v_cndmask_b32_e64 v7, 0, v7, s[4:5]
	v_readfirstlane_b32 s10, v17
	s_mul_i32 s8, s8, s10
	s_mul_hi_u32 s8, s10, s8
	v_cndmask_b32_e64 v6, 0, v6, s[4:5]
	v_cndmask_b32_e64 v13, 0, v13, s[4:5]
	v_cndmask_b32_e64 v12, 0, v12, s[4:5]
	v_cndmask_b32_e64 v11, 0, v11, s[4:5]
	v_cndmask_b32_e64 v10, 0, v10, s[4:5]
	v_cmp_gt_u32_e64 s[6:7], 16, v14
	v_add_u32_e32 v73, s46, v56
	v_add_u32_e32 v74, s46, v90
	v_add_u32_e32 v75, s46, v41
	v_add_u32_e32 v76, s46, v59
	v_add_u32_e32 v77, s46, v40
	v_add_u32_e32 v78, s46, v58
	v_add_u32_e32 v79, s46, v39
	v_add_u32_e32 v80, s46, v57
	v_add_u32_e32 v89, s44, v56
	v_add_u32_e32 v90, s44, v90
	v_add_u32_e32 v91, s44, v41
	v_add_u32_e32 v92, s44, v59
	v_add_u32_e32 v93, s44, v40
	v_add_u32_e32 v94, s44, v58
	v_add_u32_e32 v95, s44, v39
	v_add_u32_e32 v96, s44, v57
	v_or_b32_e32 v139, v19, v18
	v_or_b32_e32 v140, v19, v15
	v_or_b32_e32 v141, v20, v18
	v_or_b32_e32 v142, v20, v15
	v_or_b32_e32 v143, v21, v18
	v_or_b32_e32 v144, v21, v15
	s_ashr_i32 s55, s42, 31
	s_add_i32 s56, s10, s8
	s_sub_i32 s57, 0, s42
	v_lshlrev_b32_e32 v56, 1, v16
	s_add_i32 s58, s46, 0x3000
	s_add_i32 s59, s46, 0x2400
	s_add_i32 s60, s46, 0x3400
	s_add_i32 s61, s46, 0x2800
	s_add_i32 s64, s46, 0x3800
	s_add_i32 s65, s46, 0x2c00
	s_add_i32 s66, s46, 0x3c00
	v_add_u32_e32 v145, s46, v36
	v_add_u32_e32 v149, s46, v35
	v_add_u32_e32 v151, s46, v38
	v_add_u32_e32 v153, s46, v37
	v_lshlrev_b32_e32 v58, 1, v14
	s_movk_i32 s67, 0x7fff
	s_mov_b32 s69, 0
	s_mov_b32 s70, 0
	s_branch .LBB0_978

.LBB0_1108:
	s_or_b64 exec, exec, s[4:5]
	s_waitcnt lgkmcnt(0)
	v_mov_b32_e32 v2, v202
	s_barrier
	s_nop 0
	v_readfirstlane_b32 s4, v2
	s_ashr_i32 s4, s4, 6
	s_add_i32 s4, s4, s76
	s_cmpk_gt_i32 s4, 0x7fff
	s_cbranch_scc1 .LBB0_1111
	s_ashr_i32 s5, s4, 31
	s_lshl_b64 s[8:9], s[4:5], 11
	v_and_b32_e32 v2, 63, v2
	s_add_u32 s10, s12, s8
	s_addc_u32 s11, s13, s9
	v_lshlrev_b32_e32 v6, 3, v2
	global_load_dwordx2 v[8:9], v6, s[10:11]
	global_load_dwordx2 v[10:11], v6, s[10:11] offset:512
	global_load_dwordx2 v[14:15], v6, s[10:11] offset:1024
	global_load_dwordx2 v[34:35], v6, s[10:11] offset:1536
	v_and_b32_e32 v3, 64, v147
	v_xor_b32_e32 v5, 1, v147
	v_add_u32_e32 v21, 64, v3
	v_xor_b32_e32 v16, 2, v147
	v_cmp_lt_i32_e32 vcc, v5, v21
	v_xor_b32_e32 v17, 4, v147
	s_load_dwordx2 s[10:11], s[0:1], 0x30
	v_cndmask_b32_e32 v5, v147, v5, vcc
	v_cmp_lt_i32_e32 vcc, v16, v21
	v_xor_b32_e32 v18, 8, v147
	s_add_u32 s17, s28, 0x3103000
	v_cndmask_b32_e32 v22, v147, v16, vcc
	v_cmp_lt_i32_e32 vcc, v17, v21
	v_xor_b32_e32 v19, 16, v147
	s_addc_u32 s18, s29, 0
	v_cndmask_b32_e32 v17, v147, v17, vcc
	v_cmp_lt_i32_e32 vcc, v18, v21
	v_xor_b32_e32 v20, 32, v147
	s_add_u32 s8, s28, s8
	v_cndmask_b32_e32 v23, v147, v18, vcc
	v_cmp_lt_i32_e32 vcc, v19, v21
	v_mov_b32_e32 v7, 0
	v_lshlrev_b32_e32 v4, 2, v2
	v_cndmask_b32_e32 v19, v147, v19, vcc
	v_cmp_lt_i32_e32 vcc, v20, v21
	s_addc_u32 s9, s29, s9
	s_mov_b64 s[14:15], 0x4000000
	v_lshlrev_b32_e32 v12, 4, v2
	v_mov_b32_e32 v13, v7
	v_lshl_add_u64 v[2:3], s[12:13], 0, v[6:7]
	v_cndmask_b32_e32 v20, v147, v20, vcc
	v_or_b32_e32 v16, 0x100, v4
	v_or_b32_e32 v18, 0x200, v4
	v_or_b32_e32 v36, 0x300, v4
	s_ashr_i32 s37, s36, 31
	v_lshl_add_u64 v[6:7], s[8:9], 0, v[6:7]
	v_mov_b32_e32 v24, 0x358637bd
	s_mov_b32 s16, 0x800000
	v_lshlrev_b32_e32 v25, 2, v4
	v_lshlrev_b32_e32 v26, 2, v5
	v_lshlrev_b32_e32 v27, 2, v22
	v_lshlrev_b32_e32 v28, 2, v17
	v_lshlrev_b32_e32 v29, 2, v23
	v_lshlrev_b32_e32 v30, 2, v19
	v_lshlrev_b32_e32 v31, 2, v20
	v_lshlrev_b32_e32 v32, 2, v16
	v_lshlrev_b32_e32 v33, 2, v18
	s_waitcnt lgkmcnt(0)
	v_lshl_add_u64 v[4:5], s[10:11], 0, v[12:13]
	s_lshl_b64 s[8:9], s[36:37], 11
	v_lshl_add_u64 v[6:7], v[6:7], 0, s[14:15]
	s_waitcnt vmcnt(3)
	v_lshlrev_b32_e32 v20, 16, v8
	v_and_b32_e32 v21, 0xffff0000, v8
	v_lshlrev_b32_e32 v22, 16, v9
	v_and_b32_e32 v23, 0xffff0000, v9
	s_waitcnt vmcnt(2)
	v_lshlrev_b32_e32 v16, 16, v10
	v_and_b32_e32 v17, 0xffff0000, v10
	v_lshlrev_b32_e32 v18, 16, v11
	v_and_b32_e32 v19, 0xffff0000, v11
	s_waitcnt vmcnt(1)
	v_lshlrev_b32_e32 v12, 16, v14
	v_and_b32_e32 v13, 0xffff0000, v14
	v_lshlrev_b32_e32 v14, 16, v15
	v_and_b32_e32 v15, 0xffff0000, v15
	s_waitcnt vmcnt(0)
	v_lshlrev_b32_e32 v8, 16, v34
	v_and_b32_e32 v9, 0xffff0000, v34
	v_lshlrev_b32_e32 v10, 16, v35
	v_and_b32_e32 v11, 0xffff0000, v35
	v_lshlrev_b32_e32 v34, 2, v36
	s_mov_b32 s98, -1
	global_load_dwordx4 v[104:107], v[4:5], off
	global_load_dwordx4 v[68:71], v[4:5], off offset:1024
	global_load_dwordx4 v[80:83], v[4:5], off offset:2048
	global_load_dwordx4 v[92:95], v[4:5], off offset:3072
.LBB0_1110:
	s_ashr_i32 s5, s4, 13
	s_mov_b32 s99, s5
	s_mul_i32 s10, s5, 0x1800
	s_ashr_i32 s11, s10, 31
	s_lshl_b64 s[10:11], s[10:11], 2
	s_add_u32 s10, s17, s10
	s_addc_u32 s11, s18, s11
	s_add_i32 s19, s4, s36
	s_cmp_lt_i32 s19, 0x8000
	s_cselect_b64 s[14:15], -1, 0
	s_and_b64 vcc, s[14:15], exec
	s_cselect_b32 s4, s19, s4
	s_ashr_i32 s5, s4, 31
	v_pk_mul_f32 v[40:41], v[18:19], v[18:19]
	v_pk_mul_f32 v[42:43], v[16:17], v[16:17]
	v_pk_mul_f32 v[44:45], v[22:23], v[22:23]
	v_pk_mul_f32 v[46:47], v[20:21], v[20:21]
	s_lshl_b64 s[4:5], s[4:5], 11
	v_pk_mov_b32 v[52:53], v[46:47], v[44:45] op_sel:[1,0]
	v_mov_b32_e32 v47, v45
	v_pk_mov_b32 v[44:45], v[42:43], v[40:41] op_sel:[1,0]
	v_mov_b32_e32 v43, v41
	s_add_u32 s14, s10, 0x1000
	v_pk_add_f32 v[40:41], v[52:53], v[46:47]
	v_pk_add_f32 v[42:43], v[44:45], v[42:43]
	s_addc_u32 s15, s11, 0
	v_pk_add_f32 v[52:53], v[40:41], v[40:41] op_sel_hi:[0,1]
	v_pk_add_f32 v[54:55], v[42:43], v[42:43] op_sel_hi:[0,1]
	s_cmp_eq_u32 s99, s98
	s_cbranch_scc1 .Lnorm_keep_1
	s_mov_b32 s98, s99
	global_load_dwordx4 v[108:111], v25, s[14:15]
	global_load_dwordx4 v[112:115], v25, s[10:11]
	global_load_dwordx4 v[72:75], v32, s[14:15]
	global_load_dwordx4 v[76:79], v25, s[10:11] offset:1024
	global_load_dwordx4 v[84:87], v33, s[14:15]
	global_load_dwordx4 v[88:91], v25, s[10:11] offset:2048
	global_load_dwordx4 v[96:99], v34, s[14:15]
	global_load_dwordx4 v[100:103], v25, s[10:11] offset:3072
.Lnorm_keep_1:
	v_mul_f32_e32 v48, v12, v12
	v_mul_f32_e32 v50, v14, v14
	v_pk_fma_f32 v[48:49], v[12:13], v[12:13], v[48:49] op_sel_hi:[1,1,0]
	v_pk_fma_f32 v[50:51], v[14:15], v[14:15], v[50:51] op_sel_hi:[1,1,0]
	v_mul_f32_e32 v48, v8, v8
	v_mul_f32_e32 v50, v9, v9
	v_mul_f32_e32 v52, v10, v10
	v_mul_f32_e32 v54, v11, v11
	v_pk_add_f32 v[48:49], v[48:49], v[50:51]
	v_pk_add_f32 v[50:51], v[52:53], v[54:55]
	s_nop 0
	v_pk_add_f32 v[48:49], v[48:49], v[50:51]
	s_nop 0
	v_add_f32_e32 v35, v48, v49
	ds_bpermute_b32 v58, v26, v35
	v_lshl_add_u64 v[48:49], v[2:3], 0, s[4:5]
	global_load_dwordx2 v[50:51], v[48:49], off
	global_load_dwordx2 v[52:53], v[48:49], off offset:512
	global_load_dwordx2 v[54:55], v[48:49], off offset:1024
	global_load_dwordx2 v[56:57], v[48:49], off offset:1536
	s_waitcnt lgkmcnt(0)
	v_add_f32_e32 v35, v35, v58
	ds_bpermute_b32 v48, v27, v35
	s_waitcnt lgkmcnt(0)
	v_add_f32_e32 v35, v35, v48
	ds_bpermute_b32 v48, v28, v35
	s_waitcnt lgkmcnt(0)
	v_add_f32_e32 v35, v35, v48
	ds_bpermute_b32 v48, v29, v35
	s_waitcnt lgkmcnt(0)
	v_add_f32_e32 v35, v35, v48
	ds_bpermute_b32 v48, v30, v35
	s_waitcnt lgkmcnt(0)
	v_add_f32_e32 v35, v35, v48
	ds_bpermute_b32 v48, v31, v35
	s_waitcnt lgkmcnt(0)
	v_add_f32_e32 v35, v35, v48
	v_fmamk_f32 v35, v35, 0x3a800000, v24
	v_mul_f32_e32 v48, 0x4b800000, v35
	v_cmp_gt_f32_e64 s[4:5], s16, v35
	s_nop 1
	v_cndmask_b32_e64 v35, v35, v48, s[4:5]
	v_rsq_f32_e32 v35, v35
	s_nop 0
	v_mul_f32_e32 v48, 0x45800000, v35
	v_cndmask_b32_e64 v48, v35, v48, s[4:5]
	v_pk_mul_f32 v[22:23], v[22:23], v[48:49] op_sel_hi:[1,0]
	v_pk_mul_f32 v[20:21], v[20:21], v[48:49] op_sel_hi:[1,0]
	v_pk_mul_f32 v[18:19], v[18:19], v[48:49] op_sel_hi:[1,0]
	v_pk_mul_f32 v[16:17], v[16:17], v[48:49] op_sel_hi:[1,0]
	v_pk_mul_f32 v[14:15], v[14:15], v[48:49] op_sel_hi:[1,0]
	v_pk_mul_f32 v[12:13], v[12:13], v[48:49] op_sel_hi:[1,0]
	v_pk_mul_f32 v[58:59], v[10:11], v[48:49] op_sel_hi:[1,0]
	v_pk_mul_f32 v[48:49], v[8:9], v[48:49] op_sel_hi:[1,0]
	s_mov_b32 s4, s19
	s_waitcnt vmcnt(4)
	v_pk_mul_f32 v[20:21], v[104:105], v[20:21]
	v_pk_mul_f32 v[22:23], v[106:107], v[22:23]
	v_pk_add_f32 v[38:39], v[108:109], 1.0 op_sel_hi:[1,0]
	v_pk_add_f32 v[36:37], v[110:111], 1.0 op_sel_hi:[1,0]
	v_pk_fma_f32 v[20:21], v[38:39], v[20:21], v[112:113]
	v_pk_fma_f32 v[22:23], v[36:37], v[22:23], v[114:115]
	v_cvt_pk_bf16_f32 v20, v20, v21
	s_waitcnt vmcnt(1)
	v_lshlrev_b32_e32 v35, 16, v54
	v_cvt_pk_bf16_f32 v21, v22, v23
	global_store_dwordx2 v[6:7], v[20:21], off
	s_waitcnt vmcnt(1)
	v_pk_mul_f32 v[16:17], v[68:69], v[16:17]
	v_pk_mul_f32 v[18:19], v[70:71], v[18:19]
	v_pk_add_f32 v[22:23], v[72:73], 1.0 op_sel_hi:[1,0]
	v_pk_add_f32 v[20:21], v[74:75], 1.0 op_sel_hi:[1,0]
	v_pk_fma_f32 v[16:17], v[22:23], v[16:17], v[76:77]
	v_pk_fma_f32 v[18:19], v[20:21], v[18:19], v[78:79]
	v_cvt_pk_bf16_f32 v16, v16, v17
	s_nop 0
	v_cvt_pk_bf16_f32 v17, v18, v19
	global_store_dwordx2 v[6:7], v[16:17], off offset:512
	s_waitcnt vmcnt(2)
	v_pk_mul_f32 v[12:13], v[12:13], v[80:81]
	v_pk_mul_f32 v[14:15], v[14:15], v[82:83]
	v_pk_add_f32 v[18:19], v[84:85], 1.0 op_sel_hi:[1,0]
	v_pk_add_f32 v[16:17], v[86:87], 1.0 op_sel_hi:[1,0]
	v_pk_fma_f32 v[12:13], v[12:13], v[18:19], v[88:89]
	v_pk_fma_f32 v[14:15], v[14:15], v[16:17], v[90:91]
	v_cvt_pk_bf16_f32 v12, v12, v13
	v_lshlrev_b32_e32 v20, 16, v50
	v_cvt_pk_bf16_f32 v13, v14, v15
	global_store_dwordx2 v[6:7], v[12:13], off offset:1024
	v_and_b32_e32 v21, 0xffff0000, v50
	v_lshlrev_b32_e32 v22, 16, v51
	v_and_b32_e32 v23, 0xffff0000, v51
	v_lshlrev_b32_e32 v16, 16, v52
	v_and_b32_e32 v17, 0xffff0000, v52
	v_lshlrev_b32_e32 v18, 16, v53
	v_and_b32_e32 v19, 0xffff0000, v53
	v_and_b32_e32 v50, 0xffff0000, v54
	v_lshlrev_b32_e32 v51, 16, v55
	v_and_b32_e32 v52, 0xffff0000, v55
	v_lshlrev_b32_e32 v53, 16, v56
	v_and_b32_e32 v54, 0xffff0000, v56
	v_lshlrev_b32_e32 v55, 16, v57
	v_and_b32_e32 v56, 0xffff0000, v57
	v_mov_b32_e32 v12, v35
	v_mov_b32_e32 v13, v50
	v_mov_b32_e32 v14, v51
	v_mov_b32_e32 v15, v52
	v_mov_b32_e32 v8, v53
	v_mov_b32_e32 v9, v54
	v_mov_b32_e32 v10, v55
	v_mov_b32_e32 v11, v56
	s_waitcnt vmcnt(3)
	v_pk_mul_f32 v[36:37], v[48:49], v[92:93]
	v_pk_add_f32 v[40:41], v[96:97], 1.0 op_sel_hi:[1,0]
	v_pk_mul_f32 v[38:39], v[58:59], v[94:95]
	v_pk_add_f32 v[42:43], v[98:99], 1.0 op_sel_hi:[1,0]
	v_pk_fma_f32 v[36:37], v[36:37], v[40:41], v[100:101]
	v_pk_fma_f32 v[38:39], v[38:39], v[42:43], v[102:103]
	v_cvt_pk_bf16_f32 v36, v36, v37
	s_nop 0
	v_cvt_pk_bf16_f32 v37, v38, v39
	global_store_dwordx2 v[6:7], v[36:37], off offset:1536
	v_lshl_add_u64 v[6:7], v[6:7], 0, s[8:9]
	s_cbranch_vccnz .LBB0_1110

.LBB0_1163:
	s_or_b64 exec, exec, s[4:5]
	s_cmpk_lt_i32 s2, 0xb00
	s_cselect_b64 s[10:11], -1, 0
	s_cmpk_gt_i32 s2, 0xaff
	v_readfirstlane_b32 s5, v202
	s_waitcnt lgkmcnt(0)
	s_barrier
	s_nop 0
	s_nop 0
	s_nop 0
	s_nop 0
	s_nop 0
	s_cbranch_scc1 .LBB0_1179
	s_add_u32 s37, s28, 0x700000
	s_addc_u32 s50, s29, 0
	s_ashr_i32 s52, s2, 31
	s_lshr_b32 s4, s52, 29
	s_add_i32 s4, s2, s4
	s_lshr_b32 s14, s5, 6
	s_ashr_i32 s8, s4, 3
	s_and_b32 s4, s4, -8
	s_lshr_b32 s16, s5, 8
	s_lshl_b32 s51, s14, 10
	s_sub_i32 s4, s2, s4
	s_cmp_lt_i32 s4, 0
	s_movk_i32 s53, 0x161
	s_cselect_b32 s9, s53, 0x160
	s_mul_i32 s4, s9, s4
	s_add_i32 s4, s4, s8
	s_mul_hi_i32 s8, s4, 0x2e8ba2e9
	s_lshr_b32 s9, s8, 31
	s_ashr_i32 s8, s8, 5
	s_add_i32 s8, s8, s9
	s_lshl_b32 s9, s8, 3
	s_mulk_i32 s8, 0xb0
	s_sub_i32 s8, s4, s8
	s_sext_i32_i16 s4, s8
	s_bfe_u32 s4, s4, 0x3001c
	s_add_i32 s15, s8, s4
	s_sext_i32_i16 s4, s15
	s_and_b32 s15, s15, 0xfff8
	s_sub_i32 s8, s8, s15
	s_sext_i32_i16 s8, s8
	s_lshr_b32 s4, s4, 3
	s_add_i32 s42, s9, s8
	s_ashr_i32 s43, s42, 31
	s_bfe_i64 s[18:19], s[4:5], 0x100000
	s_lshl_b64 s[8:9], s[42:43], 19
	s_lshl_b64 s[18:19], s[18:19], 19
	s_add_u32 s46, s37, s18
	s_addc_u32 s47, s50, s19
	s_add_i32 s43, s51, 0
	s_add_i32 m0, s43, 0x10000
	v_mov_b32_e32 v151, 0
	global_load_lds_dwordx4 v150, s[46:47]
	s_add_i32 m0, s43, 0x12000
	s_add_u32 s18, s46, 0x40000
	global_load_lds_dwordx4 v154, s[46:47]
	s_addc_u32 s19, s47, 0
	s_add_i32 m0, s43, 0x14000
	v_mov_b32_e32 v155, v151
	global_load_lds_dwordx4 v150, s[18:19]
	s_add_i32 m0, s43, 0x16000
	s_add_u32 s44, s77, s8
	s_addc_u32 s45, s78, s9
	s_add_i32 s54, s43, 0x2000
	global_load_lds_dwordx4 v154, s[18:19]
	s_mov_b32 m0, s43
	s_add_u32 s8, s44, 0x40000
	global_load_lds_dwordx4 v148, s[44:45]
	s_mov_b32 m0, s54
	s_addc_u32 s9, s45, 0
	s_add_i32 s55, s43, 0x4000
	global_load_lds_dwordx4 v152, s[44:45]
	s_mov_b32 m0, s55
	s_add_i32 s56, s43, 0x6000
	global_load_lds_dwordx4 v148, s[8:9]
	s_mov_b32 m0, s56
	v_mov_b32_e32 v149, v151
	global_load_lds_dwordx4 v152, s[8:9]
	v_mov_b32_e32 v153, v151
	s_cmp_eq_u32 s16, 1
	s_mov_b32 s57, 0
	v_lshl_add_u64 v[8:9], s[46:47], 0, v[150:151]
	v_lshl_add_u64 v[6:7], s[46:47], 0, v[154:155]
	v_lshl_add_u64 v[2:3], s[44:45], 0, v[148:149]
	s_cselect_b64 s[8:9], -1, 0
	s_cmp_lg_u32 s16, 1
	v_lshl_add_u64 v[4:5], s[44:45], 0, v[152:153]
	s_cbranch_scc1 .LBB0_1166
	s_barrier

.LBB0_1311:
	s_or_b64 exec, exec, s[6:7]
	s_waitcnt lgkmcnt(0)
	v_mov_b32_e32 v2, v202
	s_barrier
	s_add_u32 s8, s28, 0x1c000000
	s_addc_u32 s9, s29, 0
	v_readfirstlane_b32 s6, v2
	s_ashr_i32 s6, s6, 6
	s_add_i32 s6, s6, s76
	s_cmpk_gt_i32 s6, 0x7fff
	s_cbranch_scc1 .LBB0_1314
	s_load_dwordx2 s[12:13], s[0:1], 0x28
	s_add_u32 s18, s28, 0x3118000
	s_addc_u32 s19, s29, 0
	v_and_b32_e32 v2, 63, v2
	v_lshlrev_b32_e32 v12, 3, v2
	s_waitcnt lgkmcnt(0)
	s_add_u32 s12, s12, 0x1000
	s_addc_u32 s13, s13, 0
	s_ashr_i32 s7, s6, 31
	s_lshl_b64 s[14:15], s[6:7], 11
	s_add_u32 s16, s8, s14
	s_addc_u32 s17, s9, s15
	global_load_dwordx2 v[14:15], v12, s[16:17]
	global_load_dwordx2 v[16:17], v12, s[16:17] offset:512
	global_load_dwordx2 v[20:21], v12, s[16:17] offset:1024
	global_load_dwordx2 v[40:41], v12, s[16:17] offset:1536
	v_and_b32_e32 v3, 64, v147
	v_xor_b32_e32 v5, 1, v147
	v_add_u32_e32 v24, 64, v3
	v_xor_b32_e32 v8, 2, v147
	v_cmp_lt_i32_e32 vcc, v5, v24
	v_xor_b32_e32 v10, 4, v147
	v_xor_b32_e32 v18, 8, v147
	v_cndmask_b32_e32 v5, v147, v5, vcc
	v_cmp_lt_i32_e32 vcc, v8, v24
	v_xor_b32_e32 v22, 16, v147
	v_xor_b32_e32 v23, 32, v147
	v_cndmask_b32_e32 v8, v147, v8, vcc
	v_cmp_lt_i32_e32 vcc, v10, v24
	v_lshlrev_b32_e32 v4, 2, v2
	v_mov_b32_e32 v13, 0
	v_cndmask_b32_e32 v10, v147, v10, vcc
	v_cmp_lt_i32_e32 vcc, v18, v24
	v_or_b32_e32 v42, 0x300, v4
	v_lshlrev_b32_e32 v6, 4, v2
	v_cndmask_b32_e32 v18, v147, v18, vcc
	v_cmp_lt_i32_e32 vcc, v22, v24
	v_mov_b32_e32 v7, v13
	v_mov_b32_e32 v9, v13
	v_cndmask_b32_e32 v25, v147, v22, vcc
	v_cmp_lt_i32_e32 vcc, v23, v24
	v_or_b32_e32 v22, 0x100, v4
	v_or_b32_e32 v24, 0x200, v4
	v_mov_b32_e32 v11, v13
	v_mov_b32_e32 v19, v13
	v_lshlrev_b32_e32 v33, 2, v8
	v_lshlrev_b32_e32 v34, 2, v10
	v_lshlrev_b32_e32 v35, 2, v18
	v_lshlrev_b32_e32 v8, 2, v22
	v_lshlrev_b32_e32 v10, 2, v24
	v_lshlrev_b32_e32 v18, 2, v42
	v_lshlrev_b32_e32 v31, 2, v4
	v_lshlrev_b32_e32 v32, 2, v5
	v_lshl_add_u64 v[4:5], s[12:13], 0, v[6:7]
	v_lshl_add_u64 v[6:7], s[12:13], 0, v[8:9]
	v_lshl_add_u64 v[8:9], s[12:13], 0, v[10:11]
	v_lshl_add_u64 v[10:11], s[12:13], 0, v[18:19]
	s_add_u32 s12, s28, s14
	s_addc_u32 s13, s29, s15
	s_mov_b64 s[16:17], 0x4000000
	v_lshl_add_u64 v[2:3], s[8:9], 0, v[12:13]
	v_cndmask_b32_e32 v23, v147, v23, vcc
	s_ashr_i32 s37, s36, 31
	v_lshl_add_u64 v[12:13], s[12:13], 0, v[12:13]
	v_mov_b32_e32 v30, 0x358637bd
	s_mov_b32 s22, 0x800000
	v_lshlrev_b32_e32 v36, 2, v25
	v_lshlrev_b32_e32 v37, 2, v23
	v_lshlrev_b32_e32 v38, 2, v22
	v_lshlrev_b32_e32 v39, 2, v24
	s_lshl_b64 s[12:13], s[36:37], 11
	v_lshl_add_u64 v[12:13], v[12:13], 0, s[16:17]
	s_waitcnt vmcnt(3)
	v_lshlrev_b32_e32 v26, 16, v14
	v_and_b32_e32 v27, 0xffff0000, v14
	v_lshlrev_b32_e32 v28, 16, v15
	v_and_b32_e32 v29, 0xffff0000, v15
	s_waitcnt vmcnt(2)
	v_lshlrev_b32_e32 v22, 16, v16
	v_and_b32_e32 v23, 0xffff0000, v16
	v_lshlrev_b32_e32 v24, 16, v17
	v_and_b32_e32 v25, 0xffff0000, v17
	s_waitcnt vmcnt(1)
	v_lshlrev_b32_e32 v18, 16, v20
	v_and_b32_e32 v19, 0xffff0000, v20
	v_lshlrev_b32_e32 v20, 16, v21
	v_and_b32_e32 v21, 0xffff0000, v21
	s_waitcnt vmcnt(0)
	v_lshlrev_b32_e32 v14, 16, v40
	v_and_b32_e32 v15, 0xffff0000, v40
	v_lshlrev_b32_e32 v16, 16, v41
	v_and_b32_e32 v17, 0xffff0000, v41
	v_lshlrev_b32_e32 v40, 2, v42
	s_mov_b32 s98, -1
	global_load_dwordx4 v[104:107], v[4:5], off
	global_load_dwordx4 v[68:71], v[6:7], off
	global_load_dwordx4 v[80:83], v[8:9], off
	global_load_dwordx4 v[92:95], v[10:11], off
.LBB0_1313:
	s_ashr_i32 s7, s6, 13
	s_mov_b32 s99, s7
	s_mul_i32 s14, s7, 0x1800
	s_ashr_i32 s15, s14, 31
	s_lshl_b64 s[14:15], s[14:15], 2
	s_add_u32 s14, s18, s14
	s_addc_u32 s15, s19, s15
	s_add_i32 s23, s6, s36
	s_cmp_lt_i32 s23, 0x8000
	s_cselect_b64 s[16:17], -1, 0
	s_and_b64 vcc, s[16:17], exec
	s_cselect_b32 s6, s23, s6
	s_ashr_i32 s7, s6, 31
	v_pk_mul_f32 v[46:47], v[24:25], v[24:25]
	v_pk_mul_f32 v[48:49], v[22:23], v[22:23]
	v_pk_mul_f32 v[50:51], v[28:29], v[28:29]
	v_pk_mul_f32 v[52:53], v[26:27], v[26:27]
	s_lshl_b64 s[6:7], s[6:7], 11
	v_pk_mov_b32 v[58:59], v[52:53], v[50:51] op_sel:[1,0]
	v_mov_b32_e32 v53, v51
	v_pk_mov_b32 v[50:51], v[48:49], v[46:47] op_sel:[1,0]
	v_mov_b32_e32 v49, v47
	s_add_u32 s16, s14, 0x1000
	v_pk_add_f32 v[46:47], v[58:59], v[52:53]
	v_pk_add_f32 v[48:49], v[50:51], v[48:49]
	s_addc_u32 s17, s15, 0
	v_pk_add_f32 v[58:59], v[46:47], v[46:47] op_sel_hi:[0,1]
	v_pk_add_f32 v[60:61], v[48:49], v[48:49] op_sel_hi:[0,1]
	s_cmp_eq_u32 s99, s98
	s_cbranch_scc1 .Lnorm_keep_2
	s_mov_b32 s98, s99
	global_load_dwordx4 v[108:111], v31, s[16:17]
	global_load_dwordx4 v[112:115], v31, s[14:15]
	global_load_dwordx4 v[72:75], v38, s[16:17]
	global_load_dwordx4 v[76:79], v31, s[14:15] offset:1024
	global_load_dwordx4 v[84:87], v39, s[16:17]
	global_load_dwordx4 v[88:91], v31, s[14:15] offset:2048
	global_load_dwordx4 v[96:99], v40, s[16:17]
	global_load_dwordx4 v[100:103], v31, s[14:15] offset:3072
.Lnorm_keep_2:
	v_mul_f32_e32 v54, v18, v18
	v_mul_f32_e32 v56, v20, v20
	v_pk_fma_f32 v[54:55], v[18:19], v[18:19], v[54:55] op_sel_hi:[1,1,0]
	v_pk_fma_f32 v[56:57], v[20:21], v[20:21], v[56:57] op_sel_hi:[1,1,0]
	v_mul_f32_e32 v54, v14, v14
	v_mul_f32_e32 v56, v15, v15
	v_mul_f32_e32 v58, v16, v16
	v_mul_f32_e32 v60, v17, v17
	v_pk_add_f32 v[54:55], v[54:55], v[56:57]
	v_pk_add_f32 v[56:57], v[58:59], v[60:61]
	s_nop 0
	v_pk_add_f32 v[54:55], v[54:55], v[56:57]
	s_nop 0
	v_add_f32_e32 v41, v54, v55
	ds_bpermute_b32 v64, v32, v41
	v_lshl_add_u64 v[54:55], v[2:3], 0, s[6:7]
	global_load_dwordx2 v[56:57], v[54:55], off
	global_load_dwordx2 v[58:59], v[54:55], off offset:512
	global_load_dwordx2 v[60:61], v[54:55], off offset:1024
	global_load_dwordx2 v[62:63], v[54:55], off offset:1536
	s_waitcnt lgkmcnt(0)
	v_add_f32_e32 v41, v41, v64
	ds_bpermute_b32 v54, v33, v41
	s_waitcnt lgkmcnt(0)
	v_add_f32_e32 v41, v41, v54
	ds_bpermute_b32 v54, v34, v41
	s_waitcnt lgkmcnt(0)
	v_add_f32_e32 v41, v41, v54
	ds_bpermute_b32 v54, v35, v41
	s_waitcnt lgkmcnt(0)
	v_add_f32_e32 v41, v41, v54
	ds_bpermute_b32 v54, v36, v41
	s_waitcnt lgkmcnt(0)
	v_add_f32_e32 v41, v41, v54
	ds_bpermute_b32 v54, v37, v41
	s_waitcnt lgkmcnt(0)
	v_add_f32_e32 v41, v41, v54
	v_fmamk_f32 v41, v41, 0x3a800000, v30
	v_mul_f32_e32 v54, 0x4b800000, v41
	v_cmp_gt_f32_e64 s[6:7], s22, v41
	s_nop 1
	v_cndmask_b32_e64 v41, v41, v54, s[6:7]
	v_rsq_f32_e32 v41, v41
	s_nop 0
	v_mul_f32_e32 v54, 0x45800000, v41
	v_cndmask_b32_e64 v54, v41, v54, s[6:7]
	v_pk_mul_f32 v[28:29], v[28:29], v[54:55] op_sel_hi:[1,0]
	v_pk_mul_f32 v[26:27], v[26:27], v[54:55] op_sel_hi:[1,0]
	v_pk_mul_f32 v[24:25], v[24:25], v[54:55] op_sel_hi:[1,0]
	v_pk_mul_f32 v[22:23], v[22:23], v[54:55] op_sel_hi:[1,0]
	v_pk_mul_f32 v[20:21], v[20:21], v[54:55] op_sel_hi:[1,0]
	v_pk_mul_f32 v[18:19], v[18:19], v[54:55] op_sel_hi:[1,0]
	v_pk_mul_f32 v[64:65], v[16:17], v[54:55] op_sel_hi:[1,0]
	v_pk_mul_f32 v[54:55], v[14:15], v[54:55] op_sel_hi:[1,0]
	s_mov_b32 s6, s23
	s_waitcnt vmcnt(4)
	v_pk_mul_f32 v[26:27], v[104:105], v[26:27]
	v_pk_mul_f32 v[28:29], v[106:107], v[28:29]
	v_pk_add_f32 v[44:45], v[108:109], 1.0 op_sel_hi:[1,0]
	v_pk_add_f32 v[42:43], v[110:111], 1.0 op_sel_hi:[1,0]
	v_pk_fma_f32 v[26:27], v[44:45], v[26:27], v[112:113]
	v_pk_fma_f32 v[28:29], v[42:43], v[28:29], v[114:115]
	v_cvt_pk_bf16_f32 v26, v26, v27
	s_waitcnt vmcnt(1)
	v_lshlrev_b32_e32 v41, 16, v60
	v_cvt_pk_bf16_f32 v27, v28, v29
	global_store_dwordx2 v[12:13], v[26:27], off
	s_waitcnt vmcnt(1)
	v_pk_mul_f32 v[22:23], v[68:69], v[22:23]
	v_pk_mul_f32 v[24:25], v[70:71], v[24:25]
	v_pk_add_f32 v[28:29], v[72:73], 1.0 op_sel_hi:[1,0]
	v_pk_add_f32 v[26:27], v[74:75], 1.0 op_sel_hi:[1,0]
	v_pk_fma_f32 v[22:23], v[28:29], v[22:23], v[76:77]
	v_pk_fma_f32 v[24:25], v[26:27], v[24:25], v[78:79]
	v_cvt_pk_bf16_f32 v22, v22, v23
	s_nop 0
	v_cvt_pk_bf16_f32 v23, v24, v25
	global_store_dwordx2 v[12:13], v[22:23], off offset:512
	s_waitcnt vmcnt(2)
	v_pk_mul_f32 v[18:19], v[18:19], v[80:81]
	v_pk_mul_f32 v[20:21], v[20:21], v[82:83]
	v_pk_add_f32 v[24:25], v[84:85], 1.0 op_sel_hi:[1,0]
	v_pk_add_f32 v[22:23], v[86:87], 1.0 op_sel_hi:[1,0]
	v_pk_fma_f32 v[18:19], v[18:19], v[24:25], v[88:89]
	v_pk_fma_f32 v[20:21], v[20:21], v[22:23], v[90:91]
	v_cvt_pk_bf16_f32 v18, v18, v19
	v_lshlrev_b32_e32 v26, 16, v56
	v_cvt_pk_bf16_f32 v19, v20, v21
	global_store_dwordx2 v[12:13], v[18:19], off offset:1024
	v_and_b32_e32 v27, 0xffff0000, v56
	v_lshlrev_b32_e32 v28, 16, v57
	v_and_b32_e32 v29, 0xffff0000, v57
	v_lshlrev_b32_e32 v22, 16, v58
	v_and_b32_e32 v23, 0xffff0000, v58
	v_lshlrev_b32_e32 v24, 16, v59
	v_and_b32_e32 v25, 0xffff0000, v59
	v_and_b32_e32 v56, 0xffff0000, v60
	v_lshlrev_b32_e32 v57, 16, v61
	v_and_b32_e32 v58, 0xffff0000, v61
	v_lshlrev_b32_e32 v59, 16, v62
	v_and_b32_e32 v60, 0xffff0000, v62
	v_lshlrev_b32_e32 v61, 16, v63
	v_and_b32_e32 v62, 0xffff0000, v63
	v_mov_b32_e32 v18, v41
	v_mov_b32_e32 v19, v56
	v_mov_b32_e32 v20, v57
	v_mov_b32_e32 v21, v58
	v_mov_b32_e32 v14, v59
	v_mov_b32_e32 v15, v60
	v_mov_b32_e32 v16, v61
	v_mov_b32_e32 v17, v62
	s_waitcnt vmcnt(3)
	v_pk_mul_f32 v[42:43], v[54:55], v[92:93]
	v_pk_add_f32 v[46:47], v[96:97], 1.0 op_sel_hi:[1,0]
	v_pk_mul_f32 v[44:45], v[64:65], v[94:95]
	v_pk_add_f32 v[48:49], v[98:99], 1.0 op_sel_hi:[1,0]
	v_pk_fma_f32 v[42:43], v[42:43], v[46:47], v[100:101]
	v_pk_fma_f32 v[44:45], v[44:45], v[48:49], v[102:103]
	v_cvt_pk_bf16_f32 v42, v42, v43
	s_nop 0
	v_cvt_pk_bf16_f32 v43, v44, v45
	global_store_dwordx2 v[12:13], v[42:43], off offset:1536
	v_lshl_add_u64 v[12:13], v[12:13], 0, s[12:13]
	s_cbranch_vccnz .LBB0_1313

.LBB0_1366:
	s_or_b64 exec, exec, s[6:7]
	s_add_u32 s69, s28, 0x4000000
	s_addc_u32 s70, s29, 0
	s_add_u32 s12, s28, 0x8000000
	s_addc_u32 s13, s29, 0
	s_cmpk_gt_i32 s2, 0x5ff
	v_readfirstlane_b32 s7, v202
	s_waitcnt lgkmcnt(0)
	s_barrier
	s_nop 0
	s_nop 0
	s_nop 0
	s_nop 0
	s_nop 0
	s_cbranch_scc1 .LBB0_1386
	s_lshr_b32 s22, s7, 6
	s_lshr_b32 s24, s7, 8
	s_lshl_b32 s37, s22, 10
	s_add_u32 s60, s28, 0x2900000
	s_addc_u32 s61, s29, 0
	s_ashr_i32 s62, s2, 31
	s_lshr_b32 s6, s62, 29
	s_add_i32 s6, s2, s6
	s_ashr_i32 s14, s6, 3
	s_and_b32 s6, s6, -8
	s_sub_i32 s6, s2, s6
	s_cmp_lt_i32 s6, 0
	s_movk_i32 s63, 0xc1
	s_cselect_b32 s15, s63, 0xc0
	s_mul_i32 s6, s15, s6
	s_add_i32 s6, s6, s14
	s_mul_hi_i32 s14, s6, 0x2aaaaaab
	s_lshr_b32 s15, s14, 31
	s_ashr_i32 s14, s14, 4
	s_add_i32 s14, s14, s15
	s_lshl_b32 s15, s14, 3
	s_mulk_i32 s14, 0x60
	s_sub_i32 s14, s6, s14
	s_bfe_i32 s6, s14, 0x80000
	s_bfe_u32 s6, s6, 0x3000c
	s_add_i32 s16, s14, s6
	s_bfe_i32 s6, s16, 0x80000
	s_and_b32 s16, s16, 0xf8
	s_sub_i32 s14, s14, s16
	s_sext_i32_i16 s6, s6
	s_sext_i32_i8 s14, s14
	s_lshr_b32 s6, s6, 3
	s_add_i32 s52, s15, s14
	s_ashr_i32 s53, s52, 31
	s_bfe_i64 s[16:17], s[6:7], 0x100000
	s_lshl_b64 s[14:15], s[52:53], 19
	s_lshl_b64 s[16:17], s[16:17], 19
	s_add_u32 s56, s60, s16
	s_addc_u32 s57, s61, s17
	s_add_i32 s64, s37, 0
	s_add_i32 m0, s64, 0x10000
	v_mov_b32_e32 v131, 0
	global_load_lds_dwordx4 v150, s[56:57]
	s_add_i32 m0, s64, 0x12000
	s_add_u32 s16, s56, 0x40000
	global_load_lds_dwordx4 v154, s[56:57]
	s_addc_u32 s17, s57, 0
	s_add_i32 m0, s64, 0x14000
	v_mov_b32_e32 v151, v131
	global_load_lds_dwordx4 v150, s[16:17]
	s_add_i32 m0, s64, 0x16000
	s_add_u32 s54, s69, s14
	s_addc_u32 s55, s70, s15
	s_add_i32 s65, s64, 0x2000
	global_load_lds_dwordx4 v154, s[16:17]
	s_mov_b32 m0, s64
	s_add_u32 s14, s54, 0x40000
	global_load_lds_dwordx4 v148, s[54:55]
	s_mov_b32 m0, s65
	s_addc_u32 s15, s55, 0
	s_add_i32 s66, s64, 0x4000
	global_load_lds_dwordx4 v152, s[54:55]
	s_mov_b32 m0, s66
	s_add_i32 s67, s64, 0x6000
	global_load_lds_dwordx4 v148, s[14:15]
	s_mov_b32 m0, s67
	v_mov_b32_e32 v155, v131
	global_load_lds_dwordx4 v152, s[14:15]
	v_mov_b32_e32 v149, v131
	v_mov_b32_e32 v153, v131
	s_cmp_eq_u32 s24, 1
	s_mov_b32 s71, 0
	v_lshl_add_u64 v[8:9], s[56:57], 0, v[150:151]
	v_lshl_add_u64 v[4:5], s[56:57], 0, v[154:155]
	s_mov_b64 s[14:15], 0x40000
	v_lshl_add_u64 v[2:3], s[54:55], 0, v[148:149]
	s_cselect_b64 s[16:17], -1, 0
	s_cmp_lg_u32 s24, 1
	v_lshl_add_u64 v[6:7], s[54:55], 0, v[152:153]
	s_cbranch_scc1 .LBB0_1369
	s_barrier

.LBB0_1438:
	s_or_b64 exec, exec, s[6:7]
	s_waitcnt lgkmcnt(0)
	v_mov_b32_e32 v2, v202
	s_barrier
	s_nop 0
	v_readfirstlane_b32 s6, v2
	s_ashr_i32 s6, s6, 6
	s_add_i32 s6, s6, s76
	s_cmpk_gt_i32 s6, 0x7fff
	s_cbranch_scc1 .LBB0_1441
	s_load_dwordx2 s[14:15], s[0:1], 0x70
	v_lshlrev_b32_e32 v3, 3, v2
	v_and_b32_e32 v3, 0x1f8, v3
	v_mov_b32_e32 v5, 0
	v_lshlrev_b32_e32 v6, 2, v3
	v_mov_b32_e32 v7, v5
	s_waitcnt lgkmcnt(0)
	v_lshl_add_u64 v[28:29], s[14:15], 0, v[6:7]
	s_mov_b64 s[14:15], 0x1000
	v_lshl_add_u64 v[30:31], v[28:29], 0, s[14:15]
	s_mov_b64 s[14:15], 0x2000
	v_lshl_add_u64 v[32:33], v[28:29], 0, s[14:15]
	s_mov_b64 s[14:15], 0x1800
	v_lshl_add_u64 v[34:35], v[28:29], 0, s[14:15]
	s_mov_b64 s[14:15], 0x2800
	s_ashr_i32 s7, s6, 31
	v_lshlrev_b32_e32 v4, 1, v3
	v_lshl_add_u64 v[36:37], v[28:29], 0, s[14:15]
	s_lshl_b64 s[14:15], s[6:7], 11
	v_lshl_add_u64 v[26:27], s[12:13], 0, v[4:5]
	v_or_b32_e32 v4, 0x400, v4
	v_and_b32_e32 v2, 63, v2
	s_add_u32 s14, s28, s14
	v_lshl_add_u64 v[38:39], s[12:13], 0, v[4:5]
	v_lshlrev_b32_e32 v4, 4, v2
	s_addc_u32 s15, s29, s15
	v_lshl_add_u64 v[2:3], s[14:15], 0, v[4:5]
	s_mov_b64 s[14:15], 0x14000400
	s_ashr_i32 s37, s36, 31
	v_lshl_add_u64 v[40:41], v[2:3], 0, s[14:15]
	s_lshl_b64 s[14:15], s[36:37], 11
	s_brev_b32 s7, 47
	s_brev_b32 s18, 31
	global_load_dwordx4 v[88:91], v[28:29], off offset:16
	global_load_dwordx4 v[92:95], v[28:29], off
	global_load_dwordx4 v[96:99], v[30:31], off offset:16
	global_load_dwordx4 v[100:103], v[30:31], off
	global_load_dwordx4 v[104:107], v[32:33], off offset:16
	global_load_dwordx4 v[108:111], v[32:33], off
	global_load_dwordx4 v[112:115], v[28:29], off offset:2048
	global_load_dwordx4 v[116:119], v[28:29], off offset:2064
	global_load_dwordx4 v[120:123], v[34:35], off
	global_load_dwordx4 v[124:127], v[34:35], off offset:16
	global_load_dwordx4 v[128:131], v[36:37], off
	global_load_dwordx4 v[132:135], v[36:37], off offset:16
	s_waitcnt vmcnt(0)
.LBB0_1440:
	s_and_b32 s19, s6, 0x1fff
	s_cmp_lt_u32 s19, 2
	s_cselect_b64 s[16:17], -1, 0
	v_cndmask_b32_e64 v44, 1.0, 0, s[16:17]
	s_and_b64 s[16:17], s[16:17], exec
	s_cselect_b32 s16, 0, -2
	s_add_i32 s16, s16, s6
	s_ashr_i32 s17, s16, 31
	s_lshl_b64 s[16:17], s[16:17], 11
	s_cmp_lg_u32 s19, 0
	v_lshl_add_u64 v[48:49], v[26:27], 0, s[16:17]
	v_lshl_add_u64 v[50:51], v[38:39], 0, s[16:17]
	s_cselect_b64 s[16:17], -1, 0
	s_cmp_lg_u64 s[16:17], 0
	s_nop 1
	v_mov_b64_e32 v[10:11], v[88:89]
	v_mov_b64_e32 v[12:13], v[90:91]
	s_nop 1
	v_mov_b64_e32 v[14:15], v[92:93]
	v_mov_b64_e32 v[16:17], v[94:95]
	s_nop 1
	v_mov_b64_e32 v[18:19], v[96:97]
	v_mov_b64_e32 v[20:21], v[98:99]
	s_nop 1
	v_mov_b64_e32 v[22:23], v[100:101]
	v_mov_b64_e32 v[24:25], v[102:103]
	s_nop 1
	v_mov_b64_e32 v[2:3], v[104:105]
	v_mov_b64_e32 v[4:5], v[106:107]
	s_nop 1
	v_mov_b64_e32 v[6:7], v[108:109]
	v_mov_b64_e32 v[8:9], v[110:111]
	global_load_dwordx4 v[60:63], v[48:49], off
	v_cndmask_b32_e64 v48, 0, 1.0, s[16:17]
	s_subb_u32 s16, s6, 0
	v_add_co_u32_e32 v42, vcc, s7, v40
	s_ashr_i32 s17, s16, 31
	s_nop 0
	v_addc_co_u32_e32 v43, vcc, -1, v41, vcc
	s_lshl_b64 s[16:17], s[16:17], 11
	global_load_dwordx4 v[52:55], v[42:43], off offset:-1024
	v_lshl_add_u64 v[64:65], v[26:27], 0, s[16:17]
	global_load_dwordx4 v[64:67], v[64:65], off
	v_add_co_u32_e32 v46, vcc, s18, v40
	v_lshl_add_u64 v[68:69], v[38:39], 0, s[16:17]
	s_nop 0
	v_addc_co_u32_e32 v47, vcc, -1, v41, vcc
	global_load_dwordx4 v[56:59], v[46:47], off offset:-1024
	s_add_i32 s6, s6, s36
	s_cmp_lt_i32 s6, 0x8000
	s_waitcnt vmcnt(4)
	v_pk_mul_f32 v[10:11], v[10:11], v[44:45] op_sel_hi:[1,0]
	s_waitcnt vmcnt(4)
	v_pk_mul_f32 v[16:17], v[16:17], v[44:45] op_sel_hi:[1,0]
	s_waitcnt vmcnt(4)
	v_pk_mul_f32 v[18:19], v[48:49], v[18:19] op_sel_hi:[0,1]
	s_waitcnt vmcnt(4)
	v_pk_mul_f32 v[24:25], v[48:49], v[24:25] op_sel_hi:[0,1]
	v_pk_mul_f32 v[22:23], v[48:49], v[22:23] op_sel_hi:[0,1]
	v_pk_mul_f32 v[14:15], v[14:15], v[44:45] op_sel_hi:[1,0]
	v_pk_mul_f32 v[20:21], v[48:49], v[20:21] op_sel_hi:[0,1]
	s_waitcnt vmcnt(4)
	v_mov_b32_e32 v73, v8
	v_mov_b32_e32 v70, v22
	v_mov_b32_e32 v72, v24
	v_mov_b32_e32 v8, v25
	v_mov_b32_e32 v74, v18
	s_waitcnt vmcnt(3)
	v_lshlrev_b32_e32 v18, 16, v60
	v_and_b32_e32 v22, 0xffff0000, v60
	s_waitcnt vmcnt(2)
	v_lshlrev_b32_e32 v79, 16, v52
	v_and_b32_e32 v81, 0xffff0000, v52
	v_lshlrev_b32_e32 v25, 16, v54
	v_and_b32_e32 v83, 0xffff0000, v54
	v_lshlrev_b32_e32 v24, 16, v61
	v_and_b32_e32 v52, 0xffff0000, v61
	v_lshlrev_b32_e32 v54, 16, v62
	v_pk_mul_f32 v[12:13], v[12:13], v[44:45] op_sel_hi:[1,0]
	v_mov_b32_e32 v71, v6
	v_mov_b32_e32 v75, v2
	v_mov_b32_e32 v77, v4
	v_mov_b32_e32 v6, v23
	v_lshlrev_b32_e32 v23, 16, v53
	v_and_b32_e32 v53, 0xffff0000, v53
	v_mov_b32_e32 v2, v19
	v_lshlrev_b32_e32 v19, 16, v55
	v_mov_b32_e32 v76, v20
	v_and_b32_e32 v55, 0xffff0000, v55
	v_mov_b32_e32 v4, v21
	v_and_b32_e32 v60, 0xffff0000, v62
	v_lshlrev_b32_e32 v61, 16, v63
	v_and_b32_e32 v62, 0xffff0000, v63
	v_fma_f32 v63, v14, v18, 0
	v_fma_f32 v84, v15, v22, 0
	v_fma_f32 v85, v16, v24, 0
	v_fma_f32 v86, v17, v52, 0
	v_fma_f32 v87, v10, v54, 0
	s_waitcnt vmcnt(1)
	v_lshlrev_b32_e32 v78, 16, v64
	v_and_b32_e32 v80, 0xffff0000, v64
	v_lshlrev_b32_e32 v22, 16, v65
	v_and_b32_e32 v52, 0xffff0000, v65
	v_lshlrev_b32_e32 v24, 16, v66
	v_and_b32_e32 v82, 0xffff0000, v66
	v_lshlrev_b32_e32 v18, 16, v67
	v_and_b32_e32 v54, 0xffff0000, v67
	v_fma_f32 v60, v11, v60, 0
	v_fma_f32 v61, v12, v61, 0
	v_fma_f32 v62, v13, v62, 0
	v_pk_mul_f32 v[10:11], v[70:71], v[78:79]
	v_pk_mul_f32 v[6:7], v[6:7], v[80:81]
	v_pk_mul_f32 v[12:13], v[72:73], v[22:23]
	v_pk_mul_f32 v[8:9], v[8:9], v[52:53]
	v_pk_mul_f32 v[14:15], v[74:75], v[24:25]
	v_pk_mul_f32 v[2:3], v[2:3], v[82:83]
	v_pk_mul_f32 v[16:17], v[76:77], v[18:19]
	v_pk_mul_f32 v[4:5], v[4:5], v[54:55]
	v_add_f32_e32 v10, v10, v63
	v_add_f32_e32 v6, v6, v84
	v_add_f32_e32 v12, v12, v85
	v_add_f32_e32 v8, v8, v86
	v_add_f32_e32 v14, v87, v14
	v_add_f32_e32 v2, v60, v2
	v_add_f32_e32 v16, v61, v16
	v_add_f32_e32 v4, v62, v4
	s_waitcnt vmcnt(0)
	v_lshlrev_b32_e32 v20, 16, v56
	v_and_b32_e32 v21, 0xffff0000, v56
	v_lshlrev_b32_e32 v45, 16, v57
	v_and_b32_e32 v49, 0xffff0000, v57
	v_lshlrev_b32_e32 v56, 16, v58
	v_and_b32_e32 v57, 0xffff0000, v58
	v_lshlrev_b32_e32 v58, 16, v59
	v_and_b32_e32 v59, 0xffff0000, v59
	v_add_f32_e32 v10, v10, v11
	v_add_f32_e32 v6, v6, v7
	v_add_f32_e32 v7, v12, v13
	v_add_f32_e32 v8, v8, v9
	v_add_f32_e32 v9, v14, v15
	v_add_f32_e32 v2, v2, v3
	v_add_f32_e32 v3, v16, v17
	v_add_f32_e32 v4, v4, v5
	v_mul_f32_e32 v5, v10, v20
	v_mul_f32_e32 v6, v6, v21
	v_mul_f32_e32 v7, v7, v45
	v_mul_f32_e32 v8, v8, v49
	v_mul_f32_e32 v9, v9, v56
	v_mul_f32_e32 v10, v2, v57
	v_mul_f32_e32 v11, v3, v58
	v_mul_f32_e32 v12, v4, v59
	v_cvt_pk_bf16_f32 v2, v5, v6
	v_cvt_pk_bf16_f32 v3, v7, v8
	v_cvt_pk_bf16_f32 v4, v9, v10
	v_cvt_pk_bf16_f32 v5, v11, v12
	global_load_dwordx4 v[6:9], v[42:43], off
	global_load_dwordx4 v[10:13], v[46:47], off
	s_waitcnt vmcnt(1)
	v_and_b32_e32 v45, 0xffff0000, v6
	global_store_dwordx4 v[40:41], v[2:5], off offset:-1024
	s_nop 1
	v_mov_b64_e32 v[2:3], v[112:113]
	v_mov_b64_e32 v[4:5], v[114:115]
	s_nop 1
	v_mov_b64_e32 v[14:15], v[116:117]
	v_mov_b64_e32 v[16:17], v[118:119]
	global_load_dwordx4 v[18:21], v[50:51], off
	s_nop 1
	v_mov_b64_e32 v[22:23], v[120:121]
	v_mov_b64_e32 v[24:25], v[122:123]
	s_nop 1
	v_mov_b64_e32 v[52:53], v[124:125]
	v_mov_b64_e32 v[54:55], v[126:127]
	global_load_dwordx4 v[56:59], v[68:69], off
	s_nop 1
	v_mov_b64_e32 v[60:61], v[128:129]
	v_mov_b64_e32 v[62:63], v[130:131]
	s_nop 1
	v_mov_b64_e32 v[64:65], v[132:133]
	v_mov_b64_e32 v[66:67], v[134:135]
	v_lshlrev_b32_e32 v49, 16, v8
	s_waitcnt vmcnt(3)
	v_lshlrev_b32_e32 v70, 16, v10
	v_and_b32_e32 v71, 0xffff0000, v10
	v_lshlrev_b32_e32 v72, 16, v11
	v_and_b32_e32 v73, 0xffff0000, v11
	v_lshlrev_b32_e32 v74, 16, v12
	v_and_b32_e32 v75, 0xffff0000, v12
	v_lshlrev_b32_e32 v76, 16, v13
	v_and_b32_e32 v77, 0xffff0000, v13
	v_lshlrev_b32_e32 v43, 16, v6
	v_lshlrev_b32_e32 v47, 16, v7
	v_and_b32_e32 v7, 0xffff0000, v7
	v_and_b32_e32 v51, 0xffff0000, v8
	v_lshlrev_b32_e32 v69, 16, v9
	v_and_b32_e32 v9, 0xffff0000, v9
	s_waitcnt vmcnt(2)
	v_pk_mul_f32 v[4:5], v[44:45], v[4:5] op_sel_hi:[0,1]
	s_waitcnt vmcnt(2)
	v_pk_mul_f32 v[10:11], v[44:45], v[16:17] op_sel_hi:[0,1]
	v_pk_mul_f32 v[12:13], v[44:45], v[14:15] op_sel_hi:[0,1]
	s_waitcnt vmcnt(1)
	v_pk_mul_f32 v[14:15], v[48:49], v[24:25] op_sel_hi:[0,1]
	v_pk_mul_f32 v[16:17], v[48:49], v[22:23] op_sel_hi:[0,1]
	v_pk_mul_f32 v[2:3], v[44:45], v[2:3] op_sel_hi:[0,1]
	v_lshlrev_b32_e32 v78, 16, v18
	v_and_b32_e32 v79, 0xffff0000, v18
	v_lshlrev_b32_e32 v80, 16, v19
	v_and_b32_e32 v81, 0xffff0000, v19
	v_lshlrev_b32_e32 v82, 16, v20
	v_and_b32_e32 v83, 0xffff0000, v20
	v_lshlrev_b32_e32 v84, 16, v21
	v_and_b32_e32 v85, 0xffff0000, v21
	s_waitcnt vmcnt(1)
	v_pk_mul_f32 v[18:19], v[48:49], v[54:55] op_sel_hi:[0,1]
	v_pk_mul_f32 v[20:21], v[48:49], v[52:53] op_sel_hi:[0,1]
	s_waitcnt vmcnt(0)
	v_lshlrev_b32_e32 v42, 16, v56
	s_waitcnt vmcnt(0)
	v_mov_b32_e32 v23, v60
	v_and_b32_e32 v44, 0xffff0000, v56
	v_lshlrev_b32_e32 v46, 16, v57
	v_mov_b32_e32 v25, v62
	v_and_b32_e32 v6, 0xffff0000, v57
	v_mov_b32_e32 v22, v16
	v_mov_b32_e32 v60, v17
	v_mov_b32_e32 v24, v14
	v_mov_b32_e32 v62, v15
	v_lshlrev_b32_e32 v48, 16, v58
	s_waitcnt vmcnt(0)
	v_mov_b32_e32 v53, v64
	v_and_b32_e32 v50, 0xffff0000, v58
	v_lshlrev_b32_e32 v68, 16, v59
	v_mov_b32_e32 v55, v66
	v_and_b32_e32 v8, 0xffff0000, v59
	v_fma_f32 v56, v2, v78, 0
	v_fma_f32 v57, v3, v79, 0
	v_fma_f32 v58, v4, v80, 0
	v_fma_f32 v59, v5, v81, 0
	v_fma_f32 v80, v10, v84, 0
	v_fma_f32 v81, v11, v85, 0
	v_mov_b32_e32 v52, v20
	v_mov_b32_e32 v64, v21
	v_mov_b32_e32 v54, v18
	v_mov_b32_e32 v66, v19
	v_pk_mul_f32 v[2:3], v[22:23], v[42:43]
	v_pk_mul_f32 v[4:5], v[60:61], v[44:45]
	v_pk_mul_f32 v[10:11], v[24:25], v[46:47]
	v_pk_mul_f32 v[6:7], v[62:63], v[6:7]
	v_fma_f32 v78, v12, v82, 0
	v_fma_f32 v79, v13, v83, 0
	v_pk_mul_f32 v[12:13], v[52:53], v[48:49]
	v_pk_mul_f32 v[14:15], v[64:65], v[50:51]
	v_pk_mul_f32 v[16:17], v[54:55], v[68:69]
	v_pk_mul_f32 v[8:9], v[66:67], v[8:9]
	v_add_f32_e32 v2, v56, v2
	v_add_f32_e32 v4, v57, v4
	v_add_f32_e32 v10, v58, v10
	v_add_f32_e32 v6, v59, v6
	v_add_f32_e32 v12, v78, v12
	v_add_f32_e32 v14, v79, v14
	v_add_f32_e32 v16, v80, v16
	v_add_f32_e32 v8, v81, v8
	v_add_f32_e32 v2, v2, v3
	v_add_f32_e32 v3, v4, v5
	v_add_f32_e32 v4, v10, v11
	v_add_f32_e32 v5, v6, v7
	v_add_f32_e32 v6, v12, v13
	v_add_f32_e32 v7, v14, v15
	v_add_f32_e32 v10, v16, v17
	v_add_f32_e32 v8, v8, v9
	v_mul_f32_e32 v2, v2, v70
	v_mul_f32_e32 v3, v3, v71
	v_mul_f32_e32 v4, v4, v72
	v_mul_f32_e32 v5, v5, v73
	v_mul_f32_e32 v6, v6, v74
	v_mul_f32_e32 v7, v7, v75
	v_mul_f32_e32 v9, v10, v76
	v_mul_f32_e32 v8, v8, v77
	v_cvt_pk_bf16_f32 v2, v2, v3
	v_cvt_pk_bf16_f32 v3, v4, v5
	v_cvt_pk_bf16_f32 v4, v6, v7
	v_cvt_pk_bf16_f32 v5, v9, v8
	global_store_dwordx4 v[40:41], v[2:5], off
	v_lshl_add_u64 v[40:41], v[40:41], 0, s[14:15]
	s_cbranch_scc1 .LBB0_1440

.LBB0_1493:
	s_or_b64 exec, exec, s[6:7]
	s_and_b64 vcc, exec, s[4:5]
	v_readfirstlane_b32 s22, v202
	s_waitcnt lgkmcnt(0)
	s_barrier
	s_nop 0
	s_nop 0
	s_nop 0
	s_nop 0
	s_nop 0
	s_nop 0
	s_nop 0
	s_nop 0
	s_nop 0
	s_nop 0
	s_nop 0
	s_nop 0
	s_nop 0
	s_nop 0
	s_nop 0
	s_nop 0
	s_nop 0
	s_nop 0
	s_nop 0
	s_nop 0
	s_nop 0
	s_nop 0
	s_nop 0
	s_nop 0
	s_nop 0
	s_nop 0
	s_nop 0
	s_nop 0
	s_cbranch_vccnz .LBB0_1517
	s_ashr_i32 s37, s2, 31
	s_lshr_b32 s6, s37, 29
	s_add_i32 s14, s2, s6
	s_and_b32 s6, s14, -8
	s_sub_i32 s16, s2, s6
	s_cmp_gt_i32 s16, -1
	s_cbranch_scc0 .LBB0_1496
	s_lshl_b32 s15, s16, 6
	s_cbranch_execz .LBB0_1497
	s_branch .LBB0_1498

.LBB0_1569:
	s_or_b64 exec, exec, s[6:7]
	s_waitcnt lgkmcnt(0)
	v_mov_b32_e32 v2, v202
	s_barrier
	s_nop 0
	v_readfirstlane_b32 s6, v2
	s_ashr_i32 s6, s6, 6
	s_add_i32 s6, s6, s76
	s_cmpk_gt_i32 s6, 0x7fff
	s_cbranch_scc1 .LBB0_1572
	s_load_dwordx2 s[14:15], s[0:1], 0x30
	v_and_b32_e32 v2, 63, v2
	v_lshlrev_b32_e32 v12, 3, v2
	v_and_b32_e32 v3, 64, v147
	v_xor_b32_e32 v5, 1, v147
	s_waitcnt lgkmcnt(0)
	s_add_u32 s16, s14, 0x1000
	s_addc_u32 s17, s15, 0
	s_ashr_i32 s7, s6, 31
	s_lshl_b64 s[14:15], s[6:7], 11
	s_add_u32 s18, s8, s14
	s_addc_u32 s19, s9, s15
	global_load_dwordx2 v[14:15], v12, s[18:19]
	global_load_dwordx2 v[16:17], v12, s[18:19] offset:512
	global_load_dwordx2 v[20:21], v12, s[18:19] offset:1024
	global_load_dwordx2 v[40:41], v12, s[18:19] offset:1536
	v_add_u32_e32 v24, 64, v3
	v_xor_b32_e32 v8, 2, v147
	v_cmp_lt_i32_e32 vcc, v5, v24
	v_xor_b32_e32 v10, 4, v147
	v_xor_b32_e32 v18, 8, v147
	v_cndmask_b32_e32 v5, v147, v5, vcc
	v_cmp_lt_i32_e32 vcc, v8, v24
	s_add_u32 s23, s28, 0x311b000
	v_xor_b32_e32 v22, 16, v147
	v_cndmask_b32_e32 v8, v147, v8, vcc
	v_cmp_lt_i32_e32 vcc, v10, v24
	s_addc_u32 s24, s29, 0
	v_xor_b32_e32 v23, 32, v147
	v_cndmask_b32_e32 v10, v147, v10, vcc
	v_cmp_lt_i32_e32 vcc, v18, v24
	v_lshlrev_b32_e32 v4, 2, v2
	s_add_u32 s14, s28, s14
	v_cndmask_b32_e32 v18, v147, v18, vcc
	v_cmp_lt_i32_e32 vcc, v22, v24
	v_mov_b32_e32 v13, 0
	v_or_b32_e32 v42, 0x300, v4
	v_cndmask_b32_e32 v25, v147, v22, vcc
	v_cmp_lt_i32_e32 vcc, v23, v24
	v_or_b32_e32 v22, 0x100, v4
	v_or_b32_e32 v24, 0x200, v4
	s_addc_u32 s15, s29, s15
	s_mov_b64 s[18:19], 0x4000000
	v_lshlrev_b32_e32 v6, 4, v2
	v_mov_b32_e32 v7, v13
	v_mov_b32_e32 v9, v13
	v_mov_b32_e32 v11, v13
	v_mov_b32_e32 v19, v13
	v_lshl_add_u64 v[2:3], s[8:9], 0, v[12:13]
	v_cndmask_b32_e32 v23, v147, v23, vcc
	v_lshlrev_b32_e32 v33, 2, v8
	v_lshlrev_b32_e32 v34, 2, v10
	v_lshlrev_b32_e32 v35, 2, v18
	v_lshlrev_b32_e32 v8, 2, v22
	v_lshlrev_b32_e32 v10, 2, v24
	v_lshlrev_b32_e32 v18, 2, v42
	s_ashr_i32 s37, s36, 31
	v_lshl_add_u64 v[12:13], s[14:15], 0, v[12:13]
	v_mov_b32_e32 v30, 0x358637bd
	s_mov_b32 s22, 0x800000
	v_lshlrev_b32_e32 v31, 2, v4
	v_lshlrev_b32_e32 v32, 2, v5
	v_lshlrev_b32_e32 v36, 2, v25
	v_lshlrev_b32_e32 v37, 2, v23
	v_lshlrev_b32_e32 v38, 2, v22
	v_lshlrev_b32_e32 v39, 2, v24
	v_lshl_add_u64 v[4:5], s[16:17], 0, v[6:7]
	v_lshl_add_u64 v[6:7], s[16:17], 0, v[8:9]
	v_lshl_add_u64 v[8:9], s[16:17], 0, v[10:11]
	v_lshl_add_u64 v[10:11], s[16:17], 0, v[18:19]
	s_lshl_b64 s[14:15], s[36:37], 11
	v_lshl_add_u64 v[12:13], v[12:13], 0, s[18:19]
	s_waitcnt vmcnt(3)
	v_lshlrev_b32_e32 v26, 16, v14
	v_and_b32_e32 v27, 0xffff0000, v14
	v_lshlrev_b32_e32 v28, 16, v15
	v_and_b32_e32 v29, 0xffff0000, v15
	s_waitcnt vmcnt(2)
	v_lshlrev_b32_e32 v22, 16, v16
	v_and_b32_e32 v23, 0xffff0000, v16
	v_lshlrev_b32_e32 v24, 16, v17
	v_and_b32_e32 v25, 0xffff0000, v17
	s_waitcnt vmcnt(1)
	v_lshlrev_b32_e32 v18, 16, v20
	v_and_b32_e32 v19, 0xffff0000, v20
	v_lshlrev_b32_e32 v20, 16, v21
	v_and_b32_e32 v21, 0xffff0000, v21
	s_waitcnt vmcnt(0)
	v_lshlrev_b32_e32 v14, 16, v40
	v_and_b32_e32 v15, 0xffff0000, v40
	v_lshlrev_b32_e32 v16, 16, v41
	v_and_b32_e32 v17, 0xffff0000, v41
	v_lshlrev_b32_e32 v40, 2, v42
	s_mov_b32 s98, -1
	global_load_dwordx4 v[104:107], v[4:5], off
	global_load_dwordx4 v[68:71], v[6:7], off
	global_load_dwordx4 v[80:83], v[8:9], off
	global_load_dwordx4 v[92:95], v[10:11], off
.LBB0_1571:
	s_ashr_i32 s7, s6, 13
	s_mov_b32 s99, s7
	s_mul_i32 s16, s7, 0x1800
	s_ashr_i32 s17, s16, 31
	s_lshl_b64 s[16:17], s[16:17], 2
	s_add_u32 s16, s23, s16
	s_addc_u32 s17, s24, s17
	s_add_i32 s25, s6, s36
	s_cmp_lt_i32 s25, 0x8000
	s_cselect_b64 s[18:19], -1, 0
	s_and_b64 vcc, s[18:19], exec
	s_cselect_b32 s6, s25, s6
	s_ashr_i32 s7, s6, 31
	v_pk_mul_f32 v[46:47], v[24:25], v[24:25]
	v_pk_mul_f32 v[48:49], v[22:23], v[22:23]
	v_pk_mul_f32 v[50:51], v[28:29], v[28:29]
	v_pk_mul_f32 v[52:53], v[26:27], v[26:27]
	s_lshl_b64 s[6:7], s[6:7], 11
	v_pk_mov_b32 v[58:59], v[52:53], v[50:51] op_sel:[1,0]
	v_mov_b32_e32 v53, v51
	v_pk_mov_b32 v[50:51], v[48:49], v[46:47] op_sel:[1,0]
	v_mov_b32_e32 v49, v47
	s_add_u32 s18, s16, 0x1000
	v_pk_add_f32 v[46:47], v[58:59], v[52:53]
	v_pk_add_f32 v[48:49], v[50:51], v[48:49]
	s_addc_u32 s19, s17, 0
	v_pk_add_f32 v[58:59], v[46:47], v[46:47] op_sel_hi:[0,1]
	v_pk_add_f32 v[60:61], v[48:49], v[48:49] op_sel_hi:[0,1]
	s_cmp_eq_u32 s99, s98
	s_cbranch_scc1 .Lnorm_keep_3
	s_mov_b32 s98, s99
	global_load_dwordx4 v[108:111], v31, s[18:19]
	global_load_dwordx4 v[112:115], v31, s[16:17]
	global_load_dwordx4 v[72:75], v38, s[18:19]
	global_load_dwordx4 v[76:79], v31, s[16:17] offset:1024
	global_load_dwordx4 v[84:87], v39, s[18:19]
	global_load_dwordx4 v[88:91], v31, s[16:17] offset:2048
	global_load_dwordx4 v[96:99], v40, s[18:19]
	global_load_dwordx4 v[100:103], v31, s[16:17] offset:3072
.Lnorm_keep_3:
	v_mul_f32_e32 v54, v18, v18
	v_mul_f32_e32 v56, v20, v20
	v_pk_fma_f32 v[54:55], v[18:19], v[18:19], v[54:55] op_sel_hi:[1,1,0]
	v_pk_fma_f32 v[56:57], v[20:21], v[20:21], v[56:57] op_sel_hi:[1,1,0]
	v_mul_f32_e32 v54, v14, v14
	v_mul_f32_e32 v56, v15, v15
	v_mul_f32_e32 v58, v16, v16
	v_mul_f32_e32 v60, v17, v17
	v_pk_add_f32 v[54:55], v[54:55], v[56:57]
	v_pk_add_f32 v[56:57], v[58:59], v[60:61]
	s_nop 0
	v_pk_add_f32 v[54:55], v[54:55], v[56:57]
	s_nop 0
	v_add_f32_e32 v41, v54, v55
	ds_bpermute_b32 v64, v32, v41
	v_lshl_add_u64 v[54:55], v[2:3], 0, s[6:7]
	global_load_dwordx2 v[56:57], v[54:55], off
	global_load_dwordx2 v[58:59], v[54:55], off offset:512
	global_load_dwordx2 v[60:61], v[54:55], off offset:1024
	global_load_dwordx2 v[62:63], v[54:55], off offset:1536
	s_waitcnt lgkmcnt(0)
	v_add_f32_e32 v41, v41, v64
	ds_bpermute_b32 v54, v33, v41
	s_waitcnt lgkmcnt(0)
	v_add_f32_e32 v41, v41, v54
	ds_bpermute_b32 v54, v34, v41
	s_waitcnt lgkmcnt(0)
	v_add_f32_e32 v41, v41, v54
	ds_bpermute_b32 v54, v35, v41
	s_waitcnt lgkmcnt(0)
	v_add_f32_e32 v41, v41, v54
	ds_bpermute_b32 v54, v36, v41
	s_waitcnt lgkmcnt(0)
	v_add_f32_e32 v41, v41, v54
	ds_bpermute_b32 v54, v37, v41
	s_waitcnt lgkmcnt(0)
	v_add_f32_e32 v41, v41, v54
	v_fmamk_f32 v41, v41, 0x3a800000, v30
	v_mul_f32_e32 v54, 0x4b800000, v41
	v_cmp_gt_f32_e64 s[6:7], s22, v41
	s_nop 1
	v_cndmask_b32_e64 v41, v41, v54, s[6:7]
	v_rsq_f32_e32 v41, v41
	s_nop 0
	v_mul_f32_e32 v54, 0x45800000, v41
	v_cndmask_b32_e64 v54, v41, v54, s[6:7]
	v_pk_mul_f32 v[28:29], v[28:29], v[54:55] op_sel_hi:[1,0]
	v_pk_mul_f32 v[26:27], v[26:27], v[54:55] op_sel_hi:[1,0]
	v_pk_mul_f32 v[24:25], v[24:25], v[54:55] op_sel_hi:[1,0]
	v_pk_mul_f32 v[22:23], v[22:23], v[54:55] op_sel_hi:[1,0]
	v_pk_mul_f32 v[20:21], v[20:21], v[54:55] op_sel_hi:[1,0]
	v_pk_mul_f32 v[18:19], v[18:19], v[54:55] op_sel_hi:[1,0]
	v_pk_mul_f32 v[64:65], v[16:17], v[54:55] op_sel_hi:[1,0]
	v_pk_mul_f32 v[54:55], v[14:15], v[54:55] op_sel_hi:[1,0]
	s_mov_b32 s6, s25
	s_waitcnt vmcnt(4)
	v_pk_mul_f32 v[26:27], v[104:105], v[26:27]
	v_pk_mul_f32 v[28:29], v[106:107], v[28:29]
	v_pk_add_f32 v[44:45], v[108:109], 1.0 op_sel_hi:[1,0]
	v_pk_add_f32 v[42:43], v[110:111], 1.0 op_sel_hi:[1,0]
	v_pk_fma_f32 v[26:27], v[44:45], v[26:27], v[112:113]
	v_pk_fma_f32 v[28:29], v[42:43], v[28:29], v[114:115]
	v_cvt_pk_bf16_f32 v26, v26, v27
	s_waitcnt vmcnt(1)
	v_lshlrev_b32_e32 v41, 16, v60
	v_cvt_pk_bf16_f32 v27, v28, v29
	global_store_dwordx2 v[12:13], v[26:27], off
	s_waitcnt vmcnt(1)
	v_pk_mul_f32 v[22:23], v[68:69], v[22:23]
	v_pk_mul_f32 v[24:25], v[70:71], v[24:25]
	v_pk_add_f32 v[28:29], v[72:73], 1.0 op_sel_hi:[1,0]
	v_pk_add_f32 v[26:27], v[74:75], 1.0 op_sel_hi:[1,0]
	v_pk_fma_f32 v[22:23], v[28:29], v[22:23], v[76:77]
	v_pk_fma_f32 v[24:25], v[26:27], v[24:25], v[78:79]
	v_cvt_pk_bf16_f32 v22, v22, v23
	s_nop 0
	v_cvt_pk_bf16_f32 v23, v24, v25
	global_store_dwordx2 v[12:13], v[22:23], off offset:512
	s_waitcnt vmcnt(2)
	v_pk_mul_f32 v[18:19], v[18:19], v[80:81]
	v_pk_mul_f32 v[20:21], v[20:21], v[82:83]
	v_pk_add_f32 v[24:25], v[84:85], 1.0 op_sel_hi:[1,0]
	v_pk_add_f32 v[22:23], v[86:87], 1.0 op_sel_hi:[1,0]
	v_pk_fma_f32 v[18:19], v[18:19], v[24:25], v[88:89]
	v_pk_fma_f32 v[20:21], v[20:21], v[22:23], v[90:91]
	v_cvt_pk_bf16_f32 v18, v18, v19
	v_lshlrev_b32_e32 v26, 16, v56
	v_cvt_pk_bf16_f32 v19, v20, v21
	global_store_dwordx2 v[12:13], v[18:19], off offset:1024
	v_and_b32_e32 v27, 0xffff0000, v56
	v_lshlrev_b32_e32 v28, 16, v57
	v_and_b32_e32 v29, 0xffff0000, v57
	v_lshlrev_b32_e32 v22, 16, v58
	v_and_b32_e32 v23, 0xffff0000, v58
	v_lshlrev_b32_e32 v24, 16, v59
	v_and_b32_e32 v25, 0xffff0000, v59
	v_and_b32_e32 v56, 0xffff0000, v60
	v_lshlrev_b32_e32 v57, 16, v61
	v_and_b32_e32 v58, 0xffff0000, v61
	v_lshlrev_b32_e32 v59, 16, v62
	v_and_b32_e32 v60, 0xffff0000, v62
	v_lshlrev_b32_e32 v61, 16, v63
	v_and_b32_e32 v62, 0xffff0000, v63
	v_mov_b32_e32 v18, v41
	v_mov_b32_e32 v19, v56
	v_mov_b32_e32 v20, v57
	v_mov_b32_e32 v21, v58
	v_mov_b32_e32 v14, v59
	v_mov_b32_e32 v15, v60
	v_mov_b32_e32 v16, v61
	v_mov_b32_e32 v17, v62
	s_waitcnt vmcnt(3)
	v_pk_mul_f32 v[42:43], v[54:55], v[92:93]
	v_pk_add_f32 v[46:47], v[96:97], 1.0 op_sel_hi:[1,0]
	v_pk_mul_f32 v[44:45], v[64:65], v[94:95]
	v_pk_add_f32 v[48:49], v[98:99], 1.0 op_sel_hi:[1,0]
	v_pk_fma_f32 v[42:43], v[42:43], v[46:47], v[100:101]
	v_pk_fma_f32 v[44:45], v[44:45], v[48:49], v[102:103]
	v_cvt_pk_bf16_f32 v42, v42, v43
	s_nop 0
	v_cvt_pk_bf16_f32 v43, v44, v45
	global_store_dwordx2 v[12:13], v[42:43], off offset:1536
	v_lshl_add_u64 v[12:13], v[12:13], 0, s[14:15]
	s_cbranch_vccnz .LBB0_1571

.LBB0_1624:
	s_or_b64 exec, exec, s[6:7]
	s_andn2_b64 vcc, exec, s[10:11]
	v_readfirstlane_b32 s7, v202
	s_waitcnt lgkmcnt(0)
	s_barrier
	s_nop 0
	s_nop 0
	s_nop 0
	s_nop 0
	s_nop 0
	s_cbranch_vccnz .LBB0_1640
	s_add_u32 s46, s28, 0x1200000
	s_addc_u32 s47, s29, 0
	s_ashr_i32 s49, s2, 31
	s_lshr_b32 s6, s49, 29
	s_add_i32 s6, s2, s6
	s_lshr_b32 s14, s7, 6
	s_ashr_i32 s10, s6, 3
	s_and_b32 s6, s6, -8
	s_lshr_b32 s16, s7, 8
	s_lshl_b32 s48, s14, 10
	s_sub_i32 s6, s2, s6
	s_cmp_lt_i32 s6, 0
	s_movk_i32 s50, 0x161
	s_cselect_b32 s11, s50, 0x160
	s_mul_i32 s6, s11, s6
	s_add_i32 s6, s6, s10
	s_mul_hi_i32 s10, s6, 0x2e8ba2e9
	s_lshr_b32 s11, s10, 31
	s_ashr_i32 s10, s10, 5
	s_add_i32 s10, s10, s11
	s_lshl_b32 s11, s10, 3
	s_mulk_i32 s10, 0xb0
	s_sub_i32 s10, s6, s10
	s_sext_i32_i16 s6, s10
	s_bfe_u32 s6, s6, 0x3001c
	s_add_i32 s15, s10, s6
	s_sext_i32_i16 s6, s15
	s_and_b32 s15, s15, 0xfff8
	s_sub_i32 s10, s10, s15
	s_sext_i32_i16 s10, s10
	s_lshr_b32 s6, s6, 3
	s_add_i32 s38, s11, s10
	s_ashr_i32 s39, s38, 31
	s_bfe_i64 s[18:19], s[6:7], 0x100000
	s_lshl_b64 s[10:11], s[38:39], 19
	s_lshl_b64 s[18:19], s[18:19], 19
	s_add_u32 s42, s46, s18
	s_addc_u32 s43, s47, s19
	s_add_i32 s39, s48, 0
	s_add_i32 m0, s39, 0x10000
	v_mov_b32_e32 v151, 0
	global_load_lds_dwordx4 v150, s[42:43]
	s_add_i32 m0, s39, 0x12000
	s_add_u32 s18, s42, 0x40000
	global_load_lds_dwordx4 v154, s[42:43]
	s_addc_u32 s19, s43, 0
	s_add_i32 m0, s39, 0x14000
	v_mov_b32_e32 v155, v151
	global_load_lds_dwordx4 v150, s[18:19]
	s_add_i32 m0, s39, 0x16000
	s_add_u32 s40, s69, s10
	s_addc_u32 s41, s70, s11
	s_add_i32 s51, s39, 0x2000
	global_load_lds_dwordx4 v154, s[18:19]
	s_mov_b32 m0, s39
	s_add_u32 s10, s40, 0x40000
	global_load_lds_dwordx4 v148, s[40:41]
	s_mov_b32 m0, s51
	s_addc_u32 s11, s41, 0
	s_add_i32 s52, s39, 0x4000
	global_load_lds_dwordx4 v152, s[40:41]
	s_mov_b32 m0, s52
	s_add_i32 s53, s39, 0x6000
	global_load_lds_dwordx4 v148, s[10:11]
	s_mov_b32 m0, s53
	v_mov_b32_e32 v149, v151
	global_load_lds_dwordx4 v152, s[10:11]
	v_mov_b32_e32 v153, v151
	s_cmp_eq_u32 s16, 1
	s_mov_b32 s54, 0
	v_lshl_add_u64 v[8:9], s[42:43], 0, v[150:151]
	v_lshl_add_u64 v[6:7], s[42:43], 0, v[154:155]
	v_lshl_add_u64 v[2:3], s[40:41], 0, v[148:149]
	s_cselect_b64 s[10:11], -1, 0
	s_cmp_lg_u32 s16, 1
	v_lshl_add_u64 v[4:5], s[40:41], 0, v[152:153]
	s_cbranch_scc1 .LBB0_1627
	s_barrier

	.amdhsa_kernel _Z10fwd_kernel6Params
		.amdhsa_group_segment_fixed_size 0
		.amdhsa_private_segment_fixed_size 0
		.amdhsa_kernarg_size 552
		.amdhsa_user_sgpr_count 2
		.amdhsa_user_sgpr_dispatch_ptr 0
		.amdhsa_user_sgpr_queue_ptr 0
		.amdhsa_user_sgpr_kernarg_segment_ptr 1
		.amdhsa_user_sgpr_dispatch_id 0
		.amdhsa_user_sgpr_kernarg_preload_length 0
		.amdhsa_user_sgpr_kernarg_preload_offset 0
		.amdhsa_user_sgpr_private_segment_size 0
		.amdhsa_uses_dynamic_stack 0
		.amdhsa_enable_private_segment 0
		.amdhsa_system_sgpr_workgroup_id_x 1
		.amdhsa_system_sgpr_workgroup_id_y 0
		.amdhsa_system_sgpr_workgroup_id_z 0
		.amdhsa_system_sgpr_workgroup_info 0
		.amdhsa_system_vgpr_workitem_id 2
		.amdhsa_next_free_vgpr 256
		.amdhsa_next_free_sgpr 100
		.amdhsa_accum_offset 256
		.amdhsa_reserve_vcc 1
		.amdhsa_float_round_mode_32 0
		.amdhsa_float_round_mode_16_64 0
		.amdhsa_float_denorm_mode_32 3
		.amdhsa_float_denorm_mode_16_64 3
		.amdhsa_dx10_clamp 1
		.amdhsa_ieee_mode 1
		.amdhsa_fp16_overflow 0
		.amdhsa_tg_split 0
		.amdhsa_exception_fp_ieee_invalid_op 0
		.amdhsa_exception_fp_denorm_src 0
		.amdhsa_exception_fp_ieee_div_zero 0
		.amdhsa_exception_fp_ieee_overflow 0
		.amdhsa_exception_fp_ieee_underflow 0
		.amdhsa_exception_fp_ieee_inexact 0
		.amdhsa_exception_int_div_zero 0
	.end_amdhsa_kernel

amdhsa.kernels:
  - .agpr_count:     0
    .args:
      - .offset:         0
        .size:           296
        .value_kind:     by_value
      - .offset:         296
        .size:           4
        .value_kind:     hidden_block_count_x
      - .offset:         300
        .size:           4
        .value_kind:     hidden_block_count_y
      - .offset:         304
        .size:           4
        .value_kind:     hidden_block_count_z
      - .offset:         308
        .size:           2
        .value_kind:     hidden_group_size_x
      - .offset:         310
        .size:           2
        .value_kind:     hidden_group_size_y
      - .offset:         312
        .size:           2
        .value_kind:     hidden_group_size_z
      - .offset:         314
        .size:           2
        .value_kind:     hidden_remainder_x
      - .offset:         316
        .size:           2
        .value_kind:     hidden_remainder_y
      - .offset:         318
        .size:           2
        .value_kind:     hidden_remainder_z
      - .offset:         336
        .size:           8
        .value_kind:     hidden_global_offset_x
      - .offset:         344
        .size:           8
        .value_kind:     hidden_global_offset_y
      - .offset:         352
        .size:           8
        .value_kind:     hidden_global_offset_z
      - .offset:         360
        .size:           2
        .value_kind:     hidden_grid_dims
      - .offset:         384
        .size:           8
        .value_kind:     hidden_multigrid_sync_arg
      - .offset:         416
        .size:           4
        .value_kind:     hidden_dynamic_lds_size
    .group_segment_fixed_size: 0
    .kernarg_segment_align: 8
    .kernarg_segment_size: 552
    .language:       OpenCL C
    .language_version:
      - 2
      - 0
    .max_flat_workgroup_size: 512
    .name:           _Z10fwd_kernel6Params
    .private_segment_fixed_size: 0
    .sgpr_count:     106
    .sgpr_spill_count: 0
    .symbol:         _Z10fwd_kernel6Params.kd
    .uniform_work_group_size: 1
    .uses_dynamic_stack: false
    .vgpr_count:     256
    .vgpr_spill_count: 0
    .wavefront_size: 64
